# v24_nt
# speedup vs baseline: 1.0126x; 1.0030x over previous
; __device__ __forceinline__ float fsigmoid(float v) { return __builtin_amdgcn_rcpf(1.0f + __builtin_amdgcn_exp2f(-LOG2E * v)); }
; __device__ __forceinline__ float fsilu(float v) { return v * fsigmoid(v); }
; __global__ void __launch_bounds__(NTHREADS, 2) fwd_megakernel(Args args) {
;     ...
;       for (int i = tid; i < 2 * DM; i += NTHREADS) sc[i] = pg8::fsilu(cvec[i]);
.LBB0_18:
	s_mov_b64 s[6:7], s[0:1]
	s_load_dwordx2 s[6:7], s[6:7], 0x8
	v_lshlrev_b32_e32 v4, 2, v221
	v_mov_b32_e32 v5, 0
	s_mov_b64 s[8:9], s[0:1]
	s_movk_i32 s14, 0x1000
	s_waitcnt lgkmcnt(0)
	v_lshl_add_u64 v[0:1], s[6:7], 0, v[4:5]
	s_mov_b64 s[10:11], s[0:1]
	v_add_co_u32_e32 v6, vcc, s14, v0
	s_load_dwordx2 s[8:9], s[8:9], 0x18
	s_mov_b64 s[12:13], s[0:1]
	v_addc_co_u32_e32 v7, vcc, 0, v1, vcc
	s_movk_i32 s14, 0x2000
	s_load_dwordx2 s[10:11], s[10:11], 0x20
	v_or_b32_e32 v3, 0x1000, v4
	global_load_dword v5, v4, s[6:7]
	global_load_dword v10, v4, s[6:7] offset:2048
	global_load_dword v11, v3, s[6:7]
	v_add_co_u32_e32 v8, vcc, s14, v0
	v_or_b32_e32 v12, 0xc00, v221
	v_or_b32_e32 v3, 0x2000, v4
	v_addc_co_u32_e32 v9, vcc, 0, v1, vcc
	v_lshlrev_b32_e32 v13, 2, v12
	global_load_dword v14, v[6:7], off offset:2048 nt
	global_load_dword v15, v3, s[6:7]
	global_load_dword v16, v[8:9], off offset:2048 nt
	global_load_dword v17, v13, s[6:7]
	v_add_u32_e32 v3, 0, v4
	s_load_dwordx2 s[12:13], s[12:13], 0xd0
	s_movk_i32 s6, 0xe00
	v_cmp_gt_u32_e32 vcc, s6, v12
	s_waitcnt vmcnt(6)
	v_mul_f32_e32 v4, 0xbfb8aa3b, v5
	s_waitcnt vmcnt(5)
	v_mul_f32_e32 v6, 0xbfb8aa3b, v10
	s_waitcnt vmcnt(4)
	v_mul_f32_e32 v7, 0xbfb8aa3b, v11
	v_exp_f32_e32 v4, v4
	v_exp_f32_e32 v6, v6
	v_exp_f32_e32 v7, v7
	s_waitcnt vmcnt(3)
	v_mul_f32_e32 v8, 0xbfb8aa3b, v14
	s_waitcnt vmcnt(2)
	v_mul_f32_e32 v9, 0xbfb8aa3b, v15
	s_waitcnt vmcnt(1)
	v_mul_f32_e32 v13, 0xbfb8aa3b, v16
	s_waitcnt vmcnt(0)
	v_mul_f32_e32 v18, 0xbfb8aa3b, v17
	v_exp_f32_e32 v8, v8
	v_exp_f32_e32 v9, v9
	v_exp_f32_e32 v13, v13
	v_exp_f32_e32 v18, v18
	v_add_f32_e32 v4, 1.0, v4
	v_add_f32_e32 v6, 1.0, v6
	v_add_f32_e32 v7, 1.0, v7
	v_rcp_f32_e32 v4, v4
	v_rcp_f32_e32 v6, v6
	v_add_f32_e32 v8, 1.0, v8
	v_rcp_f32_e32 v7, v7
	v_add_f32_e32 v9, 1.0, v9
	v_add_f32_e32 v13, 1.0, v13
	v_add_f32_e32 v18, 1.0, v18
	v_rcp_f32_e32 v8, v8
	v_rcp_f32_e32 v9, v9
	v_rcp_f32_e32 v13, v13
	v_rcp_f32_e32 v18, v18
	v_mul_f32_e32 v4, v5, v4
	v_mul_f32_e32 v5, v10, v6
	v_mul_f32_e32 v6, v11, v7
	ds_write2st64_b32 v3, v4, v5 offset0:32 offset1:40
	v_mul_f32_e32 v4, v14, v8
	v_mul_f32_e32 v5, v15, v9
	v_mul_f32_e32 v7, v16, v13
	v_mul_f32_e32 v8, v17, v18
	ds_write2st64_b32 v3, v6, v4 offset0:48 offset1:56
	ds_write2st64_b32 v3, v5, v7 offset0:64 offset1:72
	ds_write_b32 v3, v8 offset:20480
	s_and_saveexec_b64 s[6:7], vcc
	s_cbranch_execz .LBB0_20
	v_add_co_u32_e32 v0, vcc, 0x3000, v0
	s_nop 1
	v_addc_co_u32_e32 v1, vcc, 0, v1, vcc
	global_load_dword v0, v[0:1], off offset:2048 nt
	s_waitcnt vmcnt(0)
	v_mul_f32_e32 v1, 0xbfb8aa3b, v0
	v_exp_f32_e32 v1, v1
	s_nop 0
	v_add_f32_e32 v1, 1.0, v1
	v_rcp_f32_e32 v1, v1
	s_nop 0
	v_mul_f32_e32 v0, v0, v1
	ds_write_b32 v3, v0 offset:22528

; __global__ void __launch_bounds__(NTHREADS, 2) fwd_megakernel(Args args) {
;     ...
;       for (int it = bx; it < (NMOD / 64) * 4; it += G) { const int cgp = it % (NMOD / 64), kq = it / (NMOD / 64), col = cgp * 64 + lane, k0 = kq * 512 + wave * 64;
;         float a0 = 0.f, a1 = 0.f;
; #pragma unroll 32
;         for (int kk = 0; kk < 64; ++kk) { const float w = ada_w[(size_t)(k0 + kk) * NMOD + col]; a0 += w * sc[k0 + kk]; a1 += w * sc[DM + k0 + kk]; }
.LBB0_25:
	v_lshl_add_u64 v[8:9], v[4:5], 0, s[12:13]
	v_add_co_u32_e32 v76, vcc, s23, v8
	global_load_dword v0, v[8:9], off nt
	s_nop 0
	v_addc_co_u32_e32 v77, vcc, 0, v9, vcc
	v_add_co_u32_e32 v78, vcc, s24, v8
	v_mov_b32_e32 v72, s58
	s_nop 0
	v_addc_co_u32_e32 v79, vcc, 0, v9, vcc
	v_add_co_u32_e32 v80, vcc, s25, v8
	ds_read_b128 v[12:15], v72
	ds_read_b128 v[16:19], v72 offset:16
	ds_read_b128 v[20:23], v72 offset:32
	ds_read_b128 v[24:27], v72 offset:48
	v_addc_co_u32_e32 v81, vcc, 0, v9, vcc
	v_add_co_u32_e32 v82, vcc, s26, v8
	ds_read_b128 v[28:31], v72 offset:8192
	ds_read_b128 v[32:35], v72 offset:8208
	v_addc_co_u32_e32 v83, vcc, 0, v9, vcc
	v_add_co_u32_e32 v84, vcc, s27, v8
	ds_read_b128 v[36:39], v72 offset:8224
	ds_read_b128 v[40:43], v72 offset:8240
	v_addc_co_u32_e32 v85, vcc, 0, v9, vcc
	v_add_co_u32_e32 v86, vcc, s28, v8
	ds_read_b128 v[44:47], v72 offset:64
	ds_read_b128 v[48:51], v72 offset:80
	ds_read_b128 v[52:55], v72 offset:8256
	ds_read_b128 v[56:59], v72 offset:8272
	v_addc_co_u32_e32 v87, vcc, 0, v9, vcc
	v_add_co_u32_e32 v88, vcc, s29, v8
	ds_read_b128 v[60:63], v72 offset:96
	ds_read_b128 v[64:67], v72 offset:112
	ds_read_b128 v[68:71], v72 offset:8288
	ds_read_b128 v[72:75], v72 offset:8304
	v_addc_co_u32_e32 v89, vcc, 0, v9, vcc
	v_add_co_u32_e32 v90, vcc, s30, v8
	s_waitcnt lgkmcnt(14)
	v_mov_b32_e32 v136, v12
	v_addc_co_u32_e32 v91, vcc, 0, v9, vcc
	v_add_co_u32_e32 v92, vcc, s31, v8
	s_waitcnt lgkmcnt(11)
	v_mov_b32_e32 v137, v28
	v_addc_co_u32_e32 v93, vcc, 0, v9, vcc
	v_add_co_u32_e32 v94, vcc, s34, v8
	v_mov_b32_e32 v28, v13
	s_nop 0
	v_addc_co_u32_e32 v95, vcc, 0, v9, vcc
	v_add_co_u32_e32 v96, vcc, s35, v8
	v_mov_b32_e32 v12, v14
	s_nop 0
	v_addc_co_u32_e32 v97, vcc, 0, v9, vcc
	v_add_co_u32_e32 v98, vcc, s36, v8
	v_mov_b32_e32 v13, v30
	s_nop 0
	v_addc_co_u32_e32 v99, vcc, 0, v9, vcc
	v_add_co_u32_e32 v100, vcc, s37, v8
	v_mov_b32_e32 v30, v15
	s_nop 0
	v_addc_co_u32_e32 v101, vcc, 0, v9, vcc
	v_add_co_u32_e32 v102, vcc, s38, v8
	v_mov_b32_e32 v14, v16
	s_nop 0
	v_addc_co_u32_e32 v103, vcc, 0, v9, vcc
	v_add_co_u32_e32 v104, vcc, s39, v8
	s_waitcnt lgkmcnt(10)
	v_mov_b32_e32 v15, v32
	v_addc_co_u32_e32 v105, vcc, 0, v9, vcc
	v_add_co_u32_e32 v106, vcc, s40, v8
	v_mov_b32_e32 v32, v17
	s_nop 0
	v_addc_co_u32_e32 v107, vcc, 0, v9, vcc
	v_add_co_u32_e32 v108, vcc, s41, v8
	s_waitcnt vmcnt(0)
	v_pk_fma_f32 v[6:7], v[0:1], v[136:137], v[6:7] op_sel_hi:[0,1,1]
	v_addc_co_u32_e32 v109, vcc, 0, v9, vcc
	v_add_co_u32_e32 v110, vcc, s42, v8
	v_mov_b32_e32 v16, v18
	s_nop 0
	v_addc_co_u32_e32 v111, vcc, 0, v9, vcc
	v_add_co_u32_e32 v112, vcc, s43, v8
	v_mov_b32_e32 v17, v34
	s_nop 0
	v_addc_co_u32_e32 v113, vcc, 0, v9, vcc
	v_add_co_u32_e32 v114, vcc, s44, v8
	v_mov_b32_e32 v34, v19
	s_nop 0
	v_addc_co_u32_e32 v115, vcc, 0, v9, vcc
	v_add_co_u32_e32 v116, vcc, s45, v8
	v_mov_b32_e32 v18, v20
	s_nop 0
	v_addc_co_u32_e32 v117, vcc, 0, v9, vcc
	v_add_co_u32_e32 v118, vcc, s46, v8
	s_waitcnt lgkmcnt(9)
	v_mov_b32_e32 v19, v36
	v_addc_co_u32_e32 v119, vcc, 0, v9, vcc
	v_add_co_u32_e32 v120, vcc, s47, v8
	v_mov_b32_e32 v36, v21
	s_nop 0
	v_addc_co_u32_e32 v121, vcc, 0, v9, vcc
	v_add_co_u32_e32 v122, vcc, s48, v8
	v_mov_b32_e32 v20, v22
	s_nop 0
	v_addc_co_u32_e32 v123, vcc, 0, v9, vcc
	v_add_co_u32_e32 v124, vcc, s49, v8
	global_load_dword v76, v[76:77], off nt
	s_nop 0
	global_load_dword v78, v[78:79], off nt
	s_nop 0
	global_load_dword v80, v[80:81], off nt
	s_nop 0
	global_load_dword v82, v[82:83], off nt
	s_nop 0
	global_load_dword v84, v[84:85], off nt
	s_nop 0
	global_load_dword v86, v[86:87], off nt
	s_nop 0
	global_load_dword v88, v[88:89], off nt
	s_nop 0
	global_load_dword v90, v[90:91], off nt
	s_nop 0
	global_load_dword v92, v[92:93], off nt
	s_nop 0
	global_load_dword v94, v[94:95], off nt
	s_nop 0
	global_load_dword v96, v[96:97], off nt
	s_nop 0
	global_load_dword v98, v[98:99], off nt
	s_nop 0
	global_load_dword v100, v[100:101], off nt
	s_nop 0
	global_load_dword v102, v[102:103], off nt
	s_nop 0
	global_load_dword v104, v[104:105], off nt
	s_nop 0
	global_load_dword v106, v[106:107], off nt
	s_nop 0
	global_load_dword v108, v[108:109], off nt
	s_nop 0
	global_load_dword v110, v[110:111], off nt
	s_nop 0
	global_load_dword v112, v[112:113], off nt
	s_nop 0
	global_load_dword v114, v[114:115], off nt
	s_nop 0
	global_load_dword v116, v[116:117], off nt
	s_nop 0
	global_load_dword v118, v[118:119], off nt
	s_nop 0
	global_load_dword v120, v[120:121], off nt
	s_nop 0
	global_load_dword v122, v[122:123], off nt
	v_addc_co_u32_e32 v125, vcc, 0, v9, vcc
	v_add_co_u32_e32 v126, vcc, s50, v8
	v_mov_b32_e32 v21, v38
	s_nop 0
	v_addc_co_u32_e32 v127, vcc, 0, v9, vcc
	v_add_co_u32_e32 v128, vcc, s51, v8
	v_mov_b32_e32 v38, v23
	s_nop 0
	v_addc_co_u32_e32 v129, vcc, 0, v9, vcc
	v_add_co_u32_e32 v130, vcc, s52, v8
	v_mov_b32_e32 v22, v24
	s_nop 0
	v_addc_co_u32_e32 v131, vcc, 0, v9, vcc
	v_add_co_u32_e32 v132, vcc, s53, v8
	s_waitcnt lgkmcnt(8)
; __global__ void __launch_bounds__(NTHREADS, 2) fwd_megakernel(Args args) {
;     ...
;         for (int kk = 0; kk < 64; ++kk) { const float w = ada_w[(size_t)(k0 + kk) * NMOD + col]; a0 += w * sc[k0 + kk]; a1 += w * sc[DM + k0 + kk]; }
;         part[(wave * 2 + 0) * 64 + lane] = a0; part[(wave * 2 + 1) * 64 + lane] = a1;
;         __syncthreads();
;         if (tid < 128) { const int bb = tid >> 6; float sacc = (kq == 0) ? ada_b[col] : 0.f;
; #pragma unroll
;             for (int w8 = 0; w8 < 8; ++w8) sacc += part[(w8 * 2 + bb) * 64 + lane];
;             atomicAdd(mods + bb * NMOD + col, sacc); }
	v_mov_b32_e32 v23, v40
	v_addc_co_u32_e32 v133, vcc, 0, v9, vcc
	v_add_co_u32_e32 v134, vcc, s54, v8
	v_mov_b32_e32 v40, v25
	s_nop 0
	v_addc_co_u32_e32 v135, vcc, 0, v9, vcc
	v_add_co_u32_e32 v8, vcc, s55, v8
	v_mov_b32_e32 v24, v26
	s_nop 0
	v_addc_co_u32_e32 v9, vcc, 0, v9, vcc
	global_load_dword v124, v[124:125], off nt
	s_nop 0
	global_load_dword v126, v[126:127], off nt
	s_nop 0
	global_load_dword v128, v[128:129], off nt
	s_nop 0
	global_load_dword v130, v[130:131], off nt
	s_nop 0
	global_load_dword v132, v[132:133], off nt
	s_nop 0
	global_load_dword v134, v[134:135], off nt
	s_nop 0
	global_load_dword v8, v[8:9], off nt
	v_mov_b32_e32 v25, v42
	v_mov_b32_e32 v42, v27
	s_waitcnt lgkmcnt(7)
	v_mov_b32_e32 v26, v44
	s_waitcnt lgkmcnt(5)
	v_mov_b32_e32 v27, v52
	v_mov_b32_e32 v52, v45
	v_mov_b32_e32 v44, v46
	v_mov_b32_e32 v45, v54
	v_mov_b32_e32 v54, v47
	v_mov_b32_e32 v46, v48
	s_waitcnt lgkmcnt(4)
	v_mov_b32_e32 v47, v56
	v_mov_b32_e32 v56, v49
	v_mov_b32_e32 v48, v50
	v_mov_b32_e32 v49, v58
	v_mov_b32_e32 v58, v51
	s_waitcnt lgkmcnt(3)
	v_mov_b32_e32 v50, v60
	s_waitcnt lgkmcnt(1)
	v_mov_b32_e32 v51, v68
	v_mov_b32_e32 v68, v61
	v_mov_b32_e32 v60, v62
	v_mov_b32_e32 v61, v70
	v_mov_b32_e32 v70, v63
	v_mov_b32_e32 v62, v64
	s_waitcnt lgkmcnt(0)
	v_mov_b32_e32 v63, v72
	v_mov_b32_e32 v72, v65
	s_waitcnt vmcnt(30)
	v_pk_fma_f32 v[6:7], v[76:77], v[28:29], v[6:7] op_sel_hi:[0,1,1]
	s_waitcnt vmcnt(29)
	v_pk_fma_f32 v[6:7], v[78:79], v[12:13], v[6:7] op_sel_hi:[0,1,1]
	s_waitcnt vmcnt(28)
	v_pk_fma_f32 v[6:7], v[80:81], v[30:31], v[6:7] op_sel_hi:[0,1,1]
	s_waitcnt vmcnt(27)
	v_pk_fma_f32 v[6:7], v[82:83], v[14:15], v[6:7] op_sel_hi:[0,1,1]
	s_waitcnt vmcnt(26)
	v_pk_fma_f32 v[6:7], v[84:85], v[32:33], v[6:7] op_sel_hi:[0,1,1]
	s_waitcnt vmcnt(25)
	v_pk_fma_f32 v[6:7], v[86:87], v[16:17], v[6:7] op_sel_hi:[0,1,1]
	s_waitcnt vmcnt(24)
	v_pk_fma_f32 v[6:7], v[88:89], v[34:35], v[6:7] op_sel_hi:[0,1,1]
	s_waitcnt vmcnt(23)
	v_pk_fma_f32 v[6:7], v[90:91], v[18:19], v[6:7] op_sel_hi:[0,1,1]
	s_waitcnt vmcnt(22)
	v_pk_fma_f32 v[6:7], v[92:93], v[36:37], v[6:7] op_sel_hi:[0,1,1]
	s_waitcnt vmcnt(21)
	v_pk_fma_f32 v[6:7], v[94:95], v[20:21], v[6:7] op_sel_hi:[0,1,1]
	s_waitcnt vmcnt(20)
	v_pk_fma_f32 v[6:7], v[96:97], v[38:39], v[6:7] op_sel_hi:[0,1,1]
	s_waitcnt vmcnt(19)
	v_pk_fma_f32 v[6:7], v[98:99], v[22:23], v[6:7] op_sel_hi:[0,1,1]
	s_waitcnt vmcnt(18)
	v_pk_fma_f32 v[6:7], v[100:101], v[40:41], v[6:7] op_sel_hi:[0,1,1]
	s_waitcnt vmcnt(17)
	v_pk_fma_f32 v[6:7], v[102:103], v[24:25], v[6:7] op_sel_hi:[0,1,1]
	s_waitcnt vmcnt(16)
	v_pk_fma_f32 v[6:7], v[104:105], v[42:43], v[6:7] op_sel_hi:[0,1,1]
	s_waitcnt vmcnt(15)
	v_pk_fma_f32 v[6:7], v[106:107], v[26:27], v[6:7] op_sel_hi:[0,1,1]
	s_waitcnt vmcnt(14)
	v_pk_fma_f32 v[6:7], v[108:109], v[52:53], v[6:7] op_sel_hi:[0,1,1]
	s_waitcnt vmcnt(13)
	v_pk_fma_f32 v[6:7], v[110:111], v[44:45], v[6:7] op_sel_hi:[0,1,1]
	s_waitcnt vmcnt(12)
	v_pk_fma_f32 v[6:7], v[112:113], v[54:55], v[6:7] op_sel_hi:[0,1,1]
	s_waitcnt vmcnt(11)
	v_pk_fma_f32 v[6:7], v[114:115], v[46:47], v[6:7] op_sel_hi:[0,1,1]
	s_waitcnt vmcnt(10)
	v_pk_fma_f32 v[6:7], v[116:117], v[56:57], v[6:7] op_sel_hi:[0,1,1]
	s_waitcnt vmcnt(9)
	v_pk_fma_f32 v[6:7], v[118:119], v[48:49], v[6:7] op_sel_hi:[0,1,1]
	s_waitcnt vmcnt(8)
	v_pk_fma_f32 v[6:7], v[120:121], v[58:59], v[6:7] op_sel_hi:[0,1,1]
	s_waitcnt vmcnt(7)
	v_pk_fma_f32 v[6:7], v[122:123], v[50:51], v[6:7] op_sel_hi:[0,1,1]
	s_add_u32 s12, s12, 0x240000
	v_mov_b32_e32 v64, v66
	v_mov_b32_e32 v65, v74
	s_addc_u32 s13, s13, 0
	s_addk_i32 s58, 0x80
	v_mov_b32_e32 v74, v67
	s_cmp_eq_u32 s12, 0x480000
	s_waitcnt vmcnt(6)
	v_pk_fma_f32 v[6:7], v[124:125], v[68:69], v[6:7] op_sel_hi:[0,1,1]
	s_waitcnt vmcnt(5)
	v_pk_fma_f32 v[6:7], v[126:127], v[60:61], v[6:7] op_sel_hi:[0,1,1]
	s_waitcnt vmcnt(4)
	v_pk_fma_f32 v[6:7], v[128:129], v[70:71], v[6:7] op_sel_hi:[0,1,1]
	s_waitcnt vmcnt(3)
	v_pk_fma_f32 v[6:7], v[130:131], v[62:63], v[6:7] op_sel_hi:[0,1,1]
	s_waitcnt vmcnt(2)
	v_pk_fma_f32 v[6:7], v[132:133], v[72:73], v[6:7] op_sel_hi:[0,1,1]
	s_waitcnt vmcnt(1)
	v_pk_fma_f32 v[6:7], v[134:135], v[64:65], v[6:7] op_sel_hi:[0,1,1]
	s_waitcnt vmcnt(0)
	v_pk_fma_f32 v[6:7], v[8:9], v[74:75], v[6:7] op_sel_hi:[0,1,1]
	s_cbranch_scc0 .LBB0_25
	v_add_u32_e32 v0, s15, v10
	ds_write2st64_b32 v0, v6, v7 offset1:1
	s_waitcnt lgkmcnt(0)
	s_barrier
	s_and_saveexec_b64 s[12:13], s[6:7]
	s_cbranch_execz .LBB0_23
	s_mulk_i32 s57, 0x120
	s_sub_i32 s57, s56, s57
	v_lshl_or_b32 v4, s57, 6, v138
	s_add_i32 s57, s56, 0x11f
	v_ashrrev_i32_e32 v5, 31, v4
	s_cmpk_gt_u32 s57, 0x23e
	v_mov_b32_e32 v0, 0
	s_cbranch_scc1 .LBB0_22
	v_lshl_add_u64 v[6:7], v[4:5], 2, s[10:11]
	global_load_dword v0, v[6:7], off nt
	s_branch .LBB0_22

; __device__ __forceinline__ unsigned cvt_pk_bf16(float lo, float hi) { const f32x2c v = {lo, hi}; const bf16x2c b = __builtin_convertvector(v, bf16x2c); return __builtin_bit_cast(unsigned, b); }
; #define LAS __attribute__((address_space(3)))
; template <int MODE> __device__ __forceinline__ void transpose_item(const float* W, int K, int N, bf16_t* WT, LAS float* scr, int item, int lane) {
;     const int nblk = N / 32, kb = item / nblk, nb = item % nblk, k0 = 64 * kb, n0 = 32 * nb;
;     float tv[32];
; #pragma unroll
;     for (int i = 0; i < 32; ++i) tv[i] = W[(size_t)(k0 + 2 * i + (lane >> 5)) * N + n0 + (lane & 31)];
; #pragma unroll
;     for (int i = 0; i < 32; ++i) scr[(2 * i + (lane >> 5)) * 33 + (lane & 31)] = tv[i];
;     asm volatile("s_waitcnt lgkmcnt(0)" ::: "memory");
;     const int c = lane & 7, dr0 = dest_row<MODE>(n0);
; #pragma unroll
;     for (int j = 0; j < 4; ++j) { const int n = (lane >> 3) + 8 * j; const LAS float* s = scr + (8 * c) * 33 + n;
;         u32x4 o; o.x = cvt_pk_bf16(s[0 * 33], s[1 * 33]); o.y = cvt_pk_bf16(s[2 * 33], s[3 * 33]); o.z = cvt_pk_bf16(s[4 * 33], s[5 * 33]); o.w = cvt_pk_bf16(s[6 * 33], s[7 * 33]);
;         *(u32x4*)(WT + (size_t)(dr0 + n) * K + k0 + 8 * c) = o; }
;     asm volatile("s_waitcnt lgkmcnt(0)" ::: "memory");
; }
.LBB0_36:
	s_mul_hi_i32 s6, s24, 0x2e8ba2e9
	s_lshr_b32 s7, s6, 31
	s_ashr_i32 s6, s6, 6
	s_add_i32 s7, s6, s7
	s_mul_i32 s10, s7, 0xffffd400
	s_add_i32 s10, s3, s10
	s_lshl_b32 s6, s7, 6
	s_ashr_i32 s11, s10, 31
	v_add_u32_e32 v34, s6, v5
	v_lshl_add_u64 v[16:17], s[10:11], 2, v[0:1]
	v_mad_i64_i32 v[18:19], s[12:13], v34, s23, v[16:17]
	v_add_u32_e32 v20, 2, v34
	v_add_u32_e32 v22, 4, v34
	v_add_u32_e32 v24, 6, v34
	v_add_u32_e32 v26, 8, v34
	v_add_u32_e32 v28, 10, v34
	v_add_u32_e32 v30, 12, v34
	v_add_u32_e32 v32, 14, v34
	v_mad_i64_i32 v[20:21], s[12:13], v20, s23, v[16:17]
	v_mad_i64_i32 v[22:23], s[12:13], v22, s23, v[16:17]
	v_mad_i64_i32 v[24:25], s[12:13], v24, s23, v[16:17]
	v_mad_i64_i32 v[26:27], s[12:13], v26, s23, v[16:17]
	v_mad_i64_i32 v[28:29], s[12:13], v28, s23, v[16:17]
	v_mad_i64_i32 v[30:31], s[12:13], v30, s23, v[16:17]
	v_mad_i64_i32 v[32:33], s[12:13], v32, s23, v[16:17]
	global_load_dword v35, v[18:19], off nt
	global_load_dword v36, v[20:21], off nt
	global_load_dword v37, v[22:23], off nt
	global_load_dword v38, v[24:25], off nt
	global_load_dword v39, v[26:27], off nt
	global_load_dword v40, v[28:29], off nt
	global_load_dword v41, v[30:31], off nt
	global_load_dword v42, v[32:33], off nt
	v_add_u32_e32 v18, 16, v34
	v_mad_i64_i32 v[18:19], s[12:13], v18, s23, v[16:17]
	v_add_u32_e32 v20, 18, v34
	v_add_u32_e32 v22, 20, v34
	v_add_u32_e32 v24, 22, v34
	v_add_u32_e32 v26, 24, v34
	v_add_u32_e32 v28, 26, v34
	v_add_u32_e32 v30, 28, v34
	v_add_u32_e32 v32, 30, v34
	v_mad_i64_i32 v[20:21], s[12:13], v20, s23, v[16:17]
	v_mad_i64_i32 v[22:23], s[12:13], v22, s23, v[16:17]
	v_mad_i64_i32 v[24:25], s[12:13], v24, s23, v[16:17]
	v_mad_i64_i32 v[26:27], s[12:13], v26, s23, v[16:17]
	v_mad_i64_i32 v[28:29], s[12:13], v28, s23, v[16:17]
	v_mad_i64_i32 v[30:31], s[12:13], v30, s23, v[16:17]
	v_mad_i64_i32 v[32:33], s[12:13], v32, s23, v[16:17]
	global_load_dword v43, v[18:19], off nt
	global_load_dword v44, v[20:21], off nt
	global_load_dword v45, v[22:23], off nt
	global_load_dword v46, v[24:25], off nt
	global_load_dword v47, v[26:27], off nt
	global_load_dword v48, v[28:29], off nt
	global_load_dword v49, v[30:31], off nt
	global_load_dword v50, v[32:33], off nt
	v_add_u32_e32 v18, 32, v34
	v_mad_i64_i32 v[18:19], s[12:13], v18, s23, v[16:17]
	v_add_u32_e32 v20, 34, v34
	v_add_u32_e32 v22, 36, v34
	v_add_u32_e32 v24, 38, v34
	v_add_u32_e32 v26, 40, v34
	v_add_u32_e32 v28, 42, v34
	v_add_u32_e32 v30, 44, v34
	v_add_u32_e32 v32, 46, v34
	v_mad_i64_i32 v[20:21], s[12:13], v20, s23, v[16:17]
	v_mad_i64_i32 v[22:23], s[12:13], v22, s23, v[16:17]
	v_mad_i64_i32 v[24:25], s[12:13], v24, s23, v[16:17]
	v_mad_i64_i32 v[26:27], s[12:13], v26, s23, v[16:17]
	v_mad_i64_i32 v[28:29], s[12:13], v28, s23, v[16:17]
	v_mad_i64_i32 v[30:31], s[12:13], v30, s23, v[16:17]
	v_mad_i64_i32 v[32:33], s[12:13], v32, s23, v[16:17]
	global_load_dword v51, v[18:19], off nt
	global_load_dword v52, v[20:21], off nt
	global_load_dword v53, v[22:23], off nt
	global_load_dword v54, v[24:25], off nt
	global_load_dword v55, v[26:27], off nt
	global_load_dword v56, v[28:29], off nt
	global_load_dword v57, v[30:31], off nt
	global_load_dword v58, v[32:33], off nt
	v_add_u32_e32 v18, 48, v34
	v_mad_i64_i32 v[18:19], s[12:13], v18, s23, v[16:17]
	v_add_u32_e32 v20, 50, v34
	v_add_u32_e32 v22, 52, v34
	v_add_u32_e32 v24, 54, v34
	v_add_u32_e32 v26, 56, v34
	v_add_u32_e32 v28, 58, v34
	v_add_u32_e32 v30, 60, v34
	v_add_u32_e32 v32, 62, v34
	v_mad_i64_i32 v[20:21], s[12:13], v20, s23, v[16:17]
	v_mad_i64_i32 v[22:23], s[12:13], v22, s23, v[16:17]
	v_mad_i64_i32 v[24:25], s[12:13], v24, s23, v[16:17]
	v_mad_i64_i32 v[26:27], s[12:13], v26, s23, v[16:17]
	v_mad_i64_i32 v[28:29], s[12:13], v28, s23, v[16:17]
	v_mad_i64_i32 v[30:31], s[12:13], v30, s23, v[16:17]
	v_mad_i64_i32 v[16:17], s[12:13], v32, s23, v[16:17]
	global_load_dword v32, v[18:19], off nt
	global_load_dword v33, v[20:21], off nt
	global_load_dword v34, v[22:23], off nt
	global_load_dword v59, v[24:25], off nt
	global_load_dword v60, v[26:27], off nt
	global_load_dword v61, v[28:29], off nt
	global_load_dword v62, v[30:31], off nt
	global_load_dword v63, v[16:17], off nt
	s_waitcnt vmcnt(30)
	ds_write2_b32 v8, v35, v36 offset1:66
	s_waitcnt vmcnt(28)
	ds_write2_b32 v8, v37, v38 offset0:132 offset1:198
	s_waitcnt vmcnt(26)
	ds_write2_b32 v9, v39, v40 offset0:8 offset1:74
	s_waitcnt vmcnt(24)
	ds_write2_b32 v9, v41, v42 offset0:140 offset1:206
	s_waitcnt vmcnt(22)
	ds_write2_b32 v10, v43, v44 offset0:16 offset1:82
	s_waitcnt vmcnt(20)
	ds_write2_b32 v10, v45, v46 offset0:148 offset1:214
	s_waitcnt vmcnt(18)
	ds_write2_b32 v11, v47, v48 offset0:24 offset1:90
	s_waitcnt vmcnt(16)
	ds_write2_b32 v11, v49, v50 offset0:156 offset1:222
	s_waitcnt vmcnt(14)
	ds_write2_b32 v12, v51, v52 offset0:32 offset1:98
	s_waitcnt vmcnt(12)
	ds_write2_b32 v12, v53, v54 offset0:164 offset1:230
	s_waitcnt vmcnt(10)
	ds_write2_b32 v13, v55, v56 offset0:40 offset1:106
	s_waitcnt vmcnt(8)
	ds_write2_b32 v13, v57, v58 offset0:172 offset1:238
	s_waitcnt vmcnt(6)
	ds_write2_b32 v14, v32, v33 offset0:48 offset1:114
	s_waitcnt vmcnt(4)
	ds_write2_b32 v14, v34, v59 offset0:180 offset1:246
	s_waitcnt vmcnt(2)
	ds_write2_b32 v15, v60, v61 offset0:56 offset1:122
	s_waitcnt vmcnt(0)
	ds_write2_b32 v15, v62, v63 offset0:188 offset1:254
	s_mul_i32 s11, s7, 0xfffffea0
	s_waitcnt lgkmcnt(0)
	s_add_i32 s11, s24, s11
	s_cmpk_gt_i32 s11, 0xaf
	s_mov_b64 s[12:13], -1
	s_cbranch_scc0 .LBB0_38
	s_mul_i32 s11, s7, 0xffffa800
	s_add_i32 s11, s15, s11
	s_and_b32 s11, s11, 0x7fffff00
	s_and_b32 s12, s10, 0x60
	s_or_b32 s11, s12, s11
	s_bitset1_b32 s11, 7
	s_mov_b64 s[12:13], 0

; template <int MODE> __device__ __forceinline__ void transpose_item(const float* W, int K, int N, bf16_t* WT, LAS float* scr, int item, int lane) {
;     const int nblk = N / 32, kb = item / nblk, nb = item % nblk, k0 = 64 * kb, n0 = 32 * nb;
;     float tv[32];
; #pragma unroll
;     for (int i = 0; i < 32; ++i) tv[i] = W[(size_t)(k0 + 2 * i + (lane >> 5)) * N + n0 + (lane & 31)];
.LBB0_42:
	s_ashr_i32 s6, s14, 31
	s_lshr_b32 s6, s6, 26
	s_add_i32 s7, s14, s6
	s_and_b32 s6, s7, 0xffffffc0
	s_lshl_b32 s7, s7, 5
	s_and_b32 s7, s7, 0xfffff800
	v_add_u32_e32 v16, s6, v5
	s_sub_i32 s10, s3, s7
	v_add_u32_e32 v18, 2, v16
	v_add_u32_e32 v20, 4, v16
	v_add_u32_e32 v22, 6, v16
	v_add_u32_e32 v24, 8, v16
	v_add_u32_e32 v26, 10, v16
	v_add_u32_e32 v28, 12, v16
	v_add_u32_e32 v30, 14, v16
	v_add_u32_e32 v40, 24, v16
	v_add_u32_e32 v42, 26, v16
	v_ashrrev_i32_e32 v17, 31, v16
	v_add_u32_e32 v32, 16, v16
	v_add_u32_e32 v34, 18, v16
	v_add_u32_e32 v36, 20, v16
	v_add_u32_e32 v38, 22, v16
	v_add_u32_e32 v44, 28, v16
	v_add_u32_e32 v46, 30, v16
	v_add_u32_e32 v48, 32, v16
	v_add_u32_e32 v50, 34, v16
	v_add_u32_e32 v52, 36, v16
	v_add_u32_e32 v54, 38, v16
	v_add_u32_e32 v56, 40, v16
	v_add_u32_e32 v58, 42, v16
	v_add_u32_e32 v60, 44, v16
	v_add_u32_e32 v62, 46, v16
	v_add_u32_e32 v64, 48, v16
	v_add_u32_e32 v66, 50, v16
	v_add_u32_e32 v68, 52, v16
	v_add_u32_e32 v70, 54, v16
	v_add_u32_e32 v72, 56, v16
	v_add_u32_e32 v74, 58, v16
	v_add_u32_e32 v76, 60, v16
	v_add_u32_e32 v78, 62, v16
	s_ashr_i32 s11, s10, 31
	v_ashrrev_i32_e32 v19, 31, v18
	v_ashrrev_i32_e32 v21, 31, v20
	v_ashrrev_i32_e32 v23, 31, v22
	v_ashrrev_i32_e32 v25, 31, v24
	v_ashrrev_i32_e32 v27, 31, v26
	v_ashrrev_i32_e32 v29, 31, v28
	v_ashrrev_i32_e32 v31, 31, v30
	v_ashrrev_i32_e32 v41, 31, v40
	v_ashrrev_i32_e32 v43, 31, v42
	v_lshlrev_b64 v[16:17], 13, v[16:17]
	v_ashrrev_i32_e32 v33, 31, v32
	v_ashrrev_i32_e32 v35, 31, v34
	v_ashrrev_i32_e32 v37, 31, v36
	v_ashrrev_i32_e32 v39, 31, v38
	v_ashrrev_i32_e32 v45, 31, v44
	v_ashrrev_i32_e32 v47, 31, v46
	v_ashrrev_i32_e32 v49, 31, v48
	v_ashrrev_i32_e32 v51, 31, v50
	v_ashrrev_i32_e32 v53, 31, v52
	v_ashrrev_i32_e32 v55, 31, v54
	v_ashrrev_i32_e32 v57, 31, v56
	v_ashrrev_i32_e32 v59, 31, v58
	v_ashrrev_i32_e32 v61, 31, v60
	v_ashrrev_i32_e32 v63, 31, v62
	v_ashrrev_i32_e32 v65, 31, v64
	v_ashrrev_i32_e32 v67, 31, v66
	v_ashrrev_i32_e32 v69, 31, v68
	v_ashrrev_i32_e32 v71, 31, v70
	v_ashrrev_i32_e32 v73, 31, v72
	v_ashrrev_i32_e32 v75, 31, v74
	v_ashrrev_i32_e32 v77, 31, v76
	v_ashrrev_i32_e32 v79, 31, v78
	v_lshlrev_b64 v[18:19], 13, v[18:19]
	v_lshlrev_b64 v[20:21], 13, v[20:21]
	v_lshlrev_b64 v[22:23], 13, v[22:23]
	v_lshlrev_b64 v[24:25], 13, v[24:25]
	v_lshlrev_b64 v[26:27], 13, v[26:27]
	v_lshlrev_b64 v[28:29], 13, v[28:29]
	v_lshlrev_b64 v[30:31], 13, v[30:31]
	v_lshlrev_b64 v[40:41], 13, v[40:41]
	v_lshlrev_b64 v[42:43], 13, v[42:43]
	v_lshl_add_u64 v[80:81], s[10:11], 2, v[0:1]
	v_lshlrev_b64 v[32:33], 13, v[32:33]
	v_lshlrev_b64 v[34:35], 13, v[34:35]
	v_lshlrev_b64 v[36:37], 13, v[36:37]
	v_lshlrev_b64 v[38:39], 13, v[38:39]
	v_lshlrev_b64 v[44:45], 13, v[44:45]
	v_lshlrev_b64 v[46:47], 13, v[46:47]
	v_lshlrev_b64 v[48:49], 13, v[48:49]
	v_lshlrev_b64 v[50:51], 13, v[50:51]
	v_lshlrev_b64 v[52:53], 13, v[52:53]
	v_lshlrev_b64 v[54:55], 13, v[54:55]
	v_lshlrev_b64 v[56:57], 13, v[56:57]
	v_lshlrev_b64 v[58:59], 13, v[58:59]
	v_lshlrev_b64 v[60:61], 13, v[60:61]
	v_lshlrev_b64 v[62:63], 13, v[62:63]
	v_lshlrev_b64 v[64:65], 13, v[64:65]
	v_lshlrev_b64 v[66:67], 13, v[66:67]
	v_lshlrev_b64 v[68:69], 13, v[68:69]
	v_lshlrev_b64 v[70:71], 13, v[70:71]
	v_lshlrev_b64 v[72:73], 13, v[72:73]
	v_lshlrev_b64 v[74:75], 13, v[74:75]
	v_lshlrev_b64 v[76:77], 13, v[76:77]
	v_lshlrev_b64 v[78:79], 13, v[78:79]
	v_lshl_add_u64 v[16:17], v[80:81], 0, v[16:17]
	v_lshl_add_u64 v[18:19], v[80:81], 0, v[18:19]
	v_lshl_add_u64 v[20:21], v[80:81], 0, v[20:21]
	v_lshl_add_u64 v[22:23], v[80:81], 0, v[22:23]
	v_lshl_add_u64 v[24:25], v[80:81], 0, v[24:25]
	v_lshl_add_u64 v[26:27], v[80:81], 0, v[26:27]
	v_lshl_add_u64 v[28:29], v[80:81], 0, v[28:29]
	v_lshl_add_u64 v[30:31], v[80:81], 0, v[30:31]
	v_lshl_add_u64 v[40:41], v[80:81], 0, v[40:41]
	v_lshl_add_u64 v[42:43], v[80:81], 0, v[42:43]
	v_lshl_add_u64 v[32:33], v[80:81], 0, v[32:33]
	v_lshl_add_u64 v[34:35], v[80:81], 0, v[34:35]
	v_lshl_add_u64 v[36:37], v[80:81], 0, v[36:37]
	v_lshl_add_u64 v[38:39], v[80:81], 0, v[38:39]
	v_lshl_add_u64 v[44:45], v[80:81], 0, v[44:45]
	v_lshl_add_u64 v[46:47], v[80:81], 0, v[46:47]
	v_lshl_add_u64 v[48:49], v[80:81], 0, v[48:49]
	v_lshl_add_u64 v[50:51], v[80:81], 0, v[50:51]
	v_lshl_add_u64 v[52:53], v[80:81], 0, v[52:53]
	v_lshl_add_u64 v[54:55], v[80:81], 0, v[54:55]
	v_lshl_add_u64 v[56:57], v[80:81], 0, v[56:57]
	v_lshl_add_u64 v[58:59], v[80:81], 0, v[58:59]
	v_lshl_add_u64 v[60:61], v[80:81], 0, v[60:61]
	v_lshl_add_u64 v[62:63], v[80:81], 0, v[62:63]
	v_lshl_add_u64 v[64:65], v[80:81], 0, v[64:65]
	v_lshl_add_u64 v[66:67], v[80:81], 0, v[66:67]
	v_lshl_add_u64 v[68:69], v[80:81], 0, v[68:69]
	v_lshl_add_u64 v[70:71], v[80:81], 0, v[70:71]
	v_lshl_add_u64 v[72:73], v[80:81], 0, v[72:73]
	v_lshl_add_u64 v[74:75], v[80:81], 0, v[74:75]
	v_lshl_add_u64 v[76:77], v[80:81], 0, v[76:77]
	v_lshl_add_u64 v[78:79], v[80:81], 0, v[78:79]
	global_load_dword v80, v[16:17], off nt
	global_load_dword v81, v[18:19], off nt
	global_load_dword v82, v[20:21], off nt
	global_load_dword v83, v[22:23], off nt
	global_load_dword v84, v[24:25], off nt
	global_load_dword v85, v[26:27], off nt
	global_load_dword v86, v[28:29], off nt
	global_load_dword v87, v[30:31], off nt
	global_load_dword v88, v[32:33], off nt
	global_load_dword v89, v[34:35], off nt
	global_load_dword v90, v[36:37], off nt
	global_load_dword v91, v[38:39], off nt
	global_load_dword v92, v[40:41], off nt
	global_load_dword v93, v[42:43], off nt
	global_load_dword v94, v[44:45], off nt
	global_load_dword v18, v[46:47], off nt
	global_load_dword v19, v[48:49], off nt
	global_load_dword v20, v[50:51], off nt
	global_load_dword v21, v[52:53], off nt
	global_load_dword v22, v[54:55], off nt
	global_load_dword v23, v[56:57], off nt
	global_load_dword v24, v[58:59], off nt
	global_load_dword v25, v[60:61], off nt
	global_load_dword v26, v[62:63], off nt
	global_load_dword v27, v[64:65], off nt
	global_load_dword v28, v[66:67], off nt
	global_load_dword v29, v[68:69], off nt
	global_load_dword v30, v[70:71], off nt
	global_load_dword v31, v[72:73], off nt
	global_load_dword v40, v[74:75], off nt
	global_load_dword v41, v[76:77], off nt
	global_load_dword v42, v[78:79], off nt
	s_waitcnt vmcnt(30)
; __device__ __forceinline__ unsigned cvt_pk_bf16(float lo, float hi) { const f32x2c v = {lo, hi}; const bf16x2c b = __builtin_convertvector(v, bf16x2c); return __builtin_bit_cast(unsigned, b); }
; #define LAS __attribute__((address_space(3)))
; template <int MODE> __device__ __forceinline__ void transpose_item(const float* W, int K, int N, bf16_t* WT, LAS float* scr, int item, int lane) {
;     ...
;     for (int i = 0; i < 32; ++i) scr[(2 * i + (lane >> 5)) * 33 + (lane & 31)] = tv[i];
;     asm volatile("s_waitcnt lgkmcnt(0)" ::: "memory");
;     const int c = lane & 7, dr0 = dest_row<MODE>(n0);
; #pragma unroll
;     for (int j = 0; j < 4; ++j) { const int n = (lane >> 3) + 8 * j; const LAS float* s = scr + (8 * c) * 33 + n;
;         u32x4 o; o.x = cvt_pk_bf16(s[0 * 33], s[1 * 33]); o.y = cvt_pk_bf16(s[2 * 33], s[3 * 33]); o.z = cvt_pk_bf16(s[4 * 33], s[5 * 33]); o.w = cvt_pk_bf16(s[6 * 33], s[7 * 33]);
;         *(u32x4*)(WT + (size_t)(dr0 + n) * K + k0 + 8 * c) = o; }
;     asm volatile("s_waitcnt lgkmcnt(0)" ::: "memory");
	ds_write2_b32 v8, v80, v81 offset1:66
	s_waitcnt vmcnt(28)
	ds_write2_b32 v8, v82, v83 offset0:132 offset1:198
	s_waitcnt vmcnt(26)
	ds_write2_b32 v9, v84, v85 offset0:8 offset1:74
	s_waitcnt vmcnt(24)
	ds_write2_b32 v9, v86, v87 offset0:140 offset1:206
	s_waitcnt vmcnt(22)
	ds_write2_b32 v10, v88, v89 offset0:16 offset1:82
	s_waitcnt vmcnt(20)
	ds_write2_b32 v10, v90, v91 offset0:148 offset1:214
	s_waitcnt vmcnt(18)
	ds_write2_b32 v11, v92, v93 offset0:24 offset1:90
	s_waitcnt vmcnt(16)
	ds_write2_b32 v11, v94, v18 offset0:156 offset1:222
	s_waitcnt vmcnt(14)
	ds_write2_b32 v12, v19, v20 offset0:32 offset1:98
	s_waitcnt vmcnt(12)
	ds_write2_b32 v12, v21, v22 offset0:164 offset1:230
	s_waitcnt vmcnt(10)
	ds_write2_b32 v13, v23, v24 offset0:40 offset1:106
	s_waitcnt vmcnt(8)
	ds_write2_b32 v13, v25, v26 offset0:172 offset1:238
	s_waitcnt vmcnt(6)
	ds_write2_b32 v14, v27, v28 offset0:48 offset1:114
	s_waitcnt vmcnt(4)
	ds_write2_b32 v14, v29, v30 offset0:180 offset1:246
	s_waitcnt vmcnt(2)
	ds_write2_b32 v15, v31, v40 offset0:56 offset1:122
	s_waitcnt vmcnt(0)
	ds_write2_b32 v15, v41, v42 offset0:188 offset1:254
	s_waitcnt lgkmcnt(0)
	ds_read2_b32 v[20:21], v7 offset0:33 offset1:41
	ds_read2_b32 v[22:23], v7 offset1:8
	ds_read2_b32 v[24:25], v7 offset0:66 offset1:74
	ds_read2_b32 v[26:27], v7 offset0:99 offset1:107
	ds_read2_b32 v[28:29], v7 offset0:132 offset1:140
	ds_read2_b32 v[30:31], v7 offset0:165 offset1:173
	ds_read2_b32 v[40:41], v7 offset0:198 offset1:206
	ds_read2_b32 v[42:43], v7 offset0:231 offset1:239
	ds_read2_b32 v[44:45], v7 offset0:49 offset1:57
	ds_read2_b32 v[46:47], v7 offset0:16 offset1:24
	ds_read2_b32 v[48:49], v7 offset0:82 offset1:90
	ds_read2_b32 v[50:51], v7 offset0:115 offset1:123
	ds_read2_b32 v[52:53], v7 offset0:148 offset1:156
	ds_read2_b32 v[54:55], v7 offset0:181 offset1:189
	ds_read2_b32 v[56:57], v7 offset0:214 offset1:222
	ds_read2_b32 v[58:59], v7 offset0:247 offset1:255
	s_ashr_i32 s7, s6, 31
	v_add_u32_e32 v34, s10, v6
	v_lshl_add_u64 v[16:17], s[6:7], 1, v[2:3]
	v_add_u32_e32 v35, 8, v34
	v_add_u32_e32 v36, 16, v34
	v_add_u32_e32 v38, 24, v34
	v_mad_i64_i32 v[32:33], s[6:7], v34, s13, v[16:17]
	v_mad_i64_i32 v[34:35], s[6:7], v35, s13, v[16:17]
	v_mad_i64_i32 v[36:37], s[6:7], v36, s13, v[16:17]
	v_mad_i64_i32 v[38:39], s[6:7], v38, s13, v[16:17]
	s_waitcnt lgkmcnt(14)
	v_cvt_pk_bf16_f32 v16, v22, v20
	s_waitcnt lgkmcnt(12)
	v_cvt_pk_bf16_f32 v17, v24, v26
	s_waitcnt lgkmcnt(10)
	v_cvt_pk_bf16_f32 v18, v28, v30
	s_waitcnt lgkmcnt(8)
	v_cvt_pk_bf16_f32 v19, v40, v42
	v_cvt_pk_bf16_f32 v20, v23, v21
	v_cvt_pk_bf16_f32 v21, v25, v27
	v_cvt_pk_bf16_f32 v22, v29, v31
	v_cvt_pk_bf16_f32 v23, v41, v43
	s_waitcnt lgkmcnt(6)
	v_cvt_pk_bf16_f32 v24, v46, v44
	s_waitcnt lgkmcnt(4)
	v_cvt_pk_bf16_f32 v25, v48, v50
	s_waitcnt lgkmcnt(2)
	v_cvt_pk_bf16_f32 v26, v52, v54
	s_waitcnt lgkmcnt(0)
	v_cvt_pk_bf16_f32 v27, v56, v58
	v_cvt_pk_bf16_f32 v28, v47, v45
	v_cvt_pk_bf16_f32 v29, v49, v51
	v_cvt_pk_bf16_f32 v30, v53, v55
	v_cvt_pk_bf16_f32 v31, v57, v59
	global_store_dwordx4 v[32:33], v[16:19], off
	global_store_dwordx4 v[34:35], v[20:23], off
	global_store_dwordx4 v[36:37], v[24:27], off
	global_store_dwordx4 v[38:39], v[28:31], off
	s_waitcnt lgkmcnt(0)
	s_add_i32 s14, s14, s93
	s_add_i32 s3, s3, s12
	s_cmpk_lt_i32 s14, 0x1600
	s_cbranch_scc1 .LBB0_42

; template <int MODE> __device__ __forceinline__ int dest_row(int n0) {
;     ...
;     if (MODE == 2) { if (n0 >= 4096 && n0 < 6144) { const int t = n0 & ~255, s = n0 & 255; return t + 128 * ((s >> 5) & 1) + 32 * (s >> 6); } return n0; }
; template <int MODE> __device__ __forceinline__ void transpose_item(const float* W, int K, int N, bf16_t* WT, LAS float* scr, int item, int lane) {
;     const int nblk = N / 32, kb = item / nblk, nb = item % nblk, k0 = 64 * kb, n0 = 32 * nb;
;     float tv[32];
; #pragma unroll
;     for (int i = 0; i < 32; ++i) tv[i] = W[(size_t)(k0 + 2 * i + (lane >> 5)) * N + n0 + (lane & 31)];
.LBB0_45:
	s_mul_hi_i32 s8, s14, 0x2e8ba2e9
	s_lshr_b32 s9, s8, 31
	s_ashr_i32 s8, s8, 6
	s_add_i32 s9, s8, s9
	s_mul_i32 s10, s9, 0xffffd400
	s_lshl_b32 s8, s9, 6
	s_add_i32 s10, s3, s10
	v_add_u32_e32 v18, s8, v5
	s_ashr_i32 s11, s10, 31
	v_add_u32_e32 v26, 8, v18
	v_add_u32_e32 v28, 10, v18
	v_add_u32_e32 v30, 12, v18
	v_add_u32_e32 v40, 22, v18
	v_add_u32_e32 v42, 24, v18
	v_add_u32_e32 v44, 26, v18
	v_add_u32_e32 v46, 28, v18
	v_add_u32_e32 v48, 30, v18
	v_lshl_add_u64 v[16:17], s[10:11], 2, v[0:1]
	v_add_u32_e32 v20, 2, v18
	v_add_u32_e32 v22, 4, v18
	v_add_u32_e32 v24, 6, v18
	v_add_u32_e32 v32, 14, v18
	v_add_u32_e32 v34, 16, v18
	v_add_u32_e32 v36, 18, v18
	v_add_u32_e32 v38, 20, v18
	v_add_u32_e32 v50, 32, v18
	v_add_u32_e32 v52, 34, v18
	v_add_u32_e32 v54, 36, v18
	v_add_u32_e32 v56, 38, v18
	v_add_u32_e32 v58, 40, v18
	v_add_u32_e32 v60, 42, v18
	v_add_u32_e32 v62, 44, v18
	v_add_u32_e32 v64, 46, v18
	v_add_u32_e32 v66, 48, v18
	v_add_u32_e32 v68, 50, v18
	v_add_u32_e32 v70, 52, v18
	v_add_u32_e32 v72, 54, v18
	v_add_u32_e32 v74, 56, v18
	v_add_u32_e32 v76, 58, v18
	v_add_u32_e32 v78, 60, v18
	v_add_u32_e32 v80, 62, v18
	v_mad_i64_i32 v[18:19], s[22:23], v18, s13, v[16:17]
	v_mad_i64_i32 v[26:27], s[22:23], v26, s13, v[16:17]
	v_mad_i64_i32 v[28:29], s[22:23], v28, s13, v[16:17]
	v_mad_i64_i32 v[30:31], s[22:23], v30, s13, v[16:17]
	v_mad_i64_i32 v[40:41], s[22:23], v40, s13, v[16:17]
	v_mad_i64_i32 v[42:43], s[22:23], v42, s13, v[16:17]
	v_mad_i64_i32 v[44:45], s[22:23], v44, s13, v[16:17]
	v_mad_i64_i32 v[46:47], s[22:23], v46, s13, v[16:17]
	v_mad_i64_i32 v[48:49], s[22:23], v48, s13, v[16:17]
	v_mad_i64_i32 v[20:21], s[22:23], v20, s13, v[16:17]
	v_mad_i64_i32 v[22:23], s[22:23], v22, s13, v[16:17]
	v_mad_i64_i32 v[24:25], s[22:23], v24, s13, v[16:17]
	v_mad_i64_i32 v[32:33], s[22:23], v32, s13, v[16:17]
	v_mad_i64_i32 v[34:35], s[22:23], v34, s13, v[16:17]
	v_mad_i64_i32 v[36:37], s[22:23], v36, s13, v[16:17]
	v_mad_i64_i32 v[38:39], s[22:23], v38, s13, v[16:17]
	v_mad_i64_i32 v[50:51], s[22:23], v50, s13, v[16:17]
	v_mad_i64_i32 v[52:53], s[22:23], v52, s13, v[16:17]
	v_mad_i64_i32 v[54:55], s[22:23], v54, s13, v[16:17]
	v_mad_i64_i32 v[56:57], s[22:23], v56, s13, v[16:17]
	v_mad_i64_i32 v[58:59], s[22:23], v58, s13, v[16:17]
	v_mad_i64_i32 v[60:61], s[22:23], v60, s13, v[16:17]
	v_mad_i64_i32 v[62:63], s[22:23], v62, s13, v[16:17]
	v_mad_i64_i32 v[64:65], s[22:23], v64, s13, v[16:17]
	v_mad_i64_i32 v[66:67], s[22:23], v66, s13, v[16:17]
	v_mad_i64_i32 v[68:69], s[22:23], v68, s13, v[16:17]
	v_mad_i64_i32 v[70:71], s[22:23], v70, s13, v[16:17]
	v_mad_i64_i32 v[72:73], s[22:23], v72, s13, v[16:17]
	v_mad_i64_i32 v[74:75], s[22:23], v74, s13, v[16:17]
	v_mad_i64_i32 v[76:77], s[22:23], v76, s13, v[16:17]
	v_mad_i64_i32 v[78:79], s[22:23], v78, s13, v[16:17]
	v_mad_i64_i32 v[16:17], s[22:23], v80, s13, v[16:17]
	global_load_dword v80, v[18:19], off nt
	global_load_dword v81, v[20:21], off nt
	global_load_dword v82, v[22:23], off nt
	global_load_dword v83, v[24:25], off nt
	global_load_dword v84, v[26:27], off nt
	global_load_dword v85, v[28:29], off nt
	global_load_dword v86, v[30:31], off nt
	global_load_dword v87, v[32:33], off nt
	global_load_dword v88, v[34:35], off nt
	global_load_dword v89, v[36:37], off nt
	global_load_dword v90, v[38:39], off nt
	global_load_dword v91, v[40:41], off nt
	global_load_dword v92, v[42:43], off nt
	global_load_dword v93, v[44:45], off nt
	global_load_dword v94, v[46:47], off nt
	global_load_dword v26, v[48:49], off nt
	global_load_dword v27, v[50:51], off nt
	global_load_dword v28, v[52:53], off nt
	global_load_dword v29, v[54:55], off nt
	global_load_dword v30, v[56:57], off nt
	global_load_dword v31, v[58:59], off nt
	global_load_dword v40, v[60:61], off nt
	global_load_dword v41, v[62:63], off nt
	global_load_dword v42, v[64:65], off nt
	global_load_dword v43, v[66:67], off nt
	global_load_dword v44, v[68:69], off nt
	global_load_dword v45, v[70:71], off nt
	global_load_dword v46, v[72:73], off nt
	global_load_dword v47, v[74:75], off nt
	global_load_dword v95, v[76:77], off nt
	global_load_dword v48, v[78:79], off nt
	global_load_dword v49, v[16:17], off nt
	s_and_b32 s11, s7, 0x80
	s_mulk_i32 s9, 0xfea0
	s_and_b32 s15, s10, 0x1700
	s_lshr_b32 s22, s10, 1
	s_add_i32 s9, s14, s9
	s_or_b32 s11, s11, s15
	s_and_b32 s15, s22, 0x60
	s_and_b32 s9, s9, 0x7ffffc0
	s_or_b32 s11, s11, s15
	s_cmpk_eq_i32 s9, 0x80
	s_cselect_b32 s10, s11, s10
	v_add_u32_e32 v18, s10, v6
	s_ashr_i32 s9, s8, 31
	v_ashrrev_i32_e32 v19, 31, v18
	v_add_u32_e32 v20, 8, v18
	v_add_u32_e32 v22, 16, v18
	v_add_u32_e32 v24, 24, v18
	v_lshl_add_u64 v[16:17], s[8:9], 1, v[2:3]
	v_lshlrev_b64 v[18:19], 12, v[18:19]
	v_ashrrev_i32_e32 v21, 31, v20
	v_ashrrev_i32_e32 v23, 31, v22
	v_ashrrev_i32_e32 v25, 31, v24
	s_waitcnt vmcnt(30)
; __device__ __forceinline__ unsigned cvt_pk_bf16(float lo, float hi) { const f32x2c v = {lo, hi}; const bf16x2c b = __builtin_convertvector(v, bf16x2c); return __builtin_bit_cast(unsigned, b); }
; #define LAS __attribute__((address_space(3)))
; template <int MODE> __device__ __forceinline__ void transpose_item(const float* W, int K, int N, bf16_t* WT, LAS float* scr, int item, int lane) {
;     ...
;     for (int i = 0; i < 32; ++i) scr[(2 * i + (lane >> 5)) * 33 + (lane & 31)] = tv[i];
;     asm volatile("s_waitcnt lgkmcnt(0)" ::: "memory");
;     const int c = lane & 7, dr0 = dest_row<MODE>(n0);
; #pragma unroll
;     for (int j = 0; j < 4; ++j) { const int n = (lane >> 3) + 8 * j; const LAS float* s = scr + (8 * c) * 33 + n;
;         u32x4 o; o.x = cvt_pk_bf16(s[0 * 33], s[1 * 33]); o.y = cvt_pk_bf16(s[2 * 33], s[3 * 33]); o.z = cvt_pk_bf16(s[4 * 33], s[5 * 33]); o.w = cvt_pk_bf16(s[6 * 33], s[7 * 33]);
;         *(u32x4*)(WT + (size_t)(dr0 + n) * K + k0 + 8 * c) = o; }
;     asm volatile("s_waitcnt lgkmcnt(0)" ::: "memory");
	ds_write2_b32 v8, v80, v81 offset1:66
	s_waitcnt vmcnt(28)
	ds_write2_b32 v8, v82, v83 offset0:132 offset1:198
	s_waitcnt vmcnt(26)
	ds_write2_b32 v9, v84, v85 offset0:8 offset1:74
	s_waitcnt vmcnt(24)
	ds_write2_b32 v9, v86, v87 offset0:140 offset1:206
	s_waitcnt vmcnt(22)
	ds_write2_b32 v10, v88, v89 offset0:16 offset1:82
	s_waitcnt vmcnt(20)
	ds_write2_b32 v10, v90, v91 offset0:148 offset1:214
	s_waitcnt vmcnt(18)
	ds_write2_b32 v11, v92, v93 offset0:24 offset1:90
	s_waitcnt vmcnt(16)
	ds_write2_b32 v11, v94, v26 offset0:156 offset1:222
	s_waitcnt vmcnt(14)
	ds_write2_b32 v12, v27, v28 offset0:32 offset1:98
	s_waitcnt vmcnt(12)
	ds_write2_b32 v12, v29, v30 offset0:164 offset1:230
	s_waitcnt vmcnt(10)
	ds_write2_b32 v13, v31, v40 offset0:40 offset1:106
	s_waitcnt vmcnt(8)
	ds_write2_b32 v13, v41, v42 offset0:172 offset1:238
	s_waitcnt vmcnt(6)
	ds_write2_b32 v14, v43, v44 offset0:48 offset1:114
	s_waitcnt vmcnt(4)
	ds_write2_b32 v14, v45, v46 offset0:180 offset1:246
	s_waitcnt vmcnt(2)
	ds_write2_b32 v15, v47, v95 offset0:56 offset1:122
	s_waitcnt vmcnt(0)
	ds_write2_b32 v15, v48, v49 offset0:188 offset1:254
	v_lshl_add_u64 v[32:33], v[16:17], 0, v[18:19]
	v_lshlrev_b64 v[18:19], 12, v[20:21]
	v_lshlrev_b64 v[20:21], 12, v[22:23]
	v_lshlrev_b64 v[22:23], 12, v[24:25]
	s_waitcnt lgkmcnt(0)
	v_lshl_add_u64 v[36:37], v[16:17], 0, v[20:21]
	v_lshl_add_u64 v[38:39], v[16:17], 0, v[22:23]
	ds_read2_b32 v[20:21], v7 offset0:33 offset1:41
	ds_read2_b32 v[22:23], v7 offset1:8
	ds_read2_b32 v[24:25], v7 offset0:66 offset1:74
	ds_read2_b32 v[26:27], v7 offset0:99 offset1:107
	ds_read2_b32 v[28:29], v7 offset0:132 offset1:140
	ds_read2_b32 v[30:31], v7 offset0:165 offset1:173
	ds_read2_b32 v[40:41], v7 offset0:198 offset1:206
	ds_read2_b32 v[42:43], v7 offset0:231 offset1:239
	ds_read2_b32 v[44:45], v7 offset0:49 offset1:57
	ds_read2_b32 v[46:47], v7 offset0:16 offset1:24
	ds_read2_b32 v[48:49], v7 offset0:82 offset1:90
	ds_read2_b32 v[50:51], v7 offset0:115 offset1:123
	ds_read2_b32 v[52:53], v7 offset0:148 offset1:156
	ds_read2_b32 v[54:55], v7 offset0:181 offset1:189
	ds_read2_b32 v[56:57], v7 offset0:214 offset1:222
	ds_read2_b32 v[58:59], v7 offset0:247 offset1:255
	v_lshl_add_u64 v[34:35], v[16:17], 0, v[18:19]
	s_waitcnt lgkmcnt(14)
	v_cvt_pk_bf16_f32 v16, v22, v20
	s_waitcnt lgkmcnt(12)
	v_cvt_pk_bf16_f32 v17, v24, v26
	s_waitcnt lgkmcnt(10)
	v_cvt_pk_bf16_f32 v18, v28, v30
	s_waitcnt lgkmcnt(8)
	v_cvt_pk_bf16_f32 v19, v40, v42
	v_cvt_pk_bf16_f32 v20, v23, v21
	v_cvt_pk_bf16_f32 v21, v25, v27
	v_cvt_pk_bf16_f32 v22, v29, v31
	v_cvt_pk_bf16_f32 v23, v41, v43
	s_waitcnt lgkmcnt(6)
	v_cvt_pk_bf16_f32 v24, v46, v44
	s_waitcnt lgkmcnt(4)
	v_cvt_pk_bf16_f32 v25, v48, v50
	s_waitcnt lgkmcnt(2)
	v_cvt_pk_bf16_f32 v26, v52, v54
	s_waitcnt lgkmcnt(0)
	v_cvt_pk_bf16_f32 v27, v56, v58
	v_cvt_pk_bf16_f32 v28, v47, v45
	v_cvt_pk_bf16_f32 v29, v49, v51
	v_cvt_pk_bf16_f32 v30, v53, v55
	v_cvt_pk_bf16_f32 v31, v57, v59
	global_store_dwordx4 v[32:33], v[16:19], off
	global_store_dwordx4 v[34:35], v[20:23], off
	global_store_dwordx4 v[36:37], v[24:27], off
	global_store_dwordx4 v[38:39], v[28:31], off
	s_waitcnt lgkmcnt(0)
	s_add_i32 s14, s14, s93
	s_add_i32 s3, s3, s6
	s_add_i32 s7, s7, s12
	s_cmpk_lt_i32 s14, 0x2c00
	s_cbranch_scc1 .LBB0_45

; template <int MODE> __device__ __forceinline__ void transpose_item(const float* W, int K, int N, bf16_t* WT, LAS float* scr, int item, int lane) {
;     const int nblk = N / 32, kb = item / nblk, nb = item % nblk, k0 = 64 * kb, n0 = 32 * nb;
;     float tv[32];
; #pragma unroll
;     for (int i = 0; i < 32; ++i) tv[i] = W[(size_t)(k0 + 2 * i + (lane >> 5)) * N + n0 + (lane & 31)];
.LBB0_48:
	s_ashr_i32 s10, s7, 31
	s_lshr_b32 s10, s10, 26
	s_add_i32 s11, s7, s10
	s_and_b32 s10, s11, 0xffffffc0
	s_lshl_b32 s11, s11, 5
	s_and_b32 s11, s11, 0xfffff800
	v_add_u32_e32 v16, s10, v5
	s_sub_i32 s12, s3, s11
	v_add_u32_e32 v26, 10, v16
	v_add_u32_e32 v28, 12, v16
	v_add_u32_e32 v30, 14, v16
	v_add_u32_e32 v40, 24, v16
	v_add_u32_e32 v42, 26, v16
	v_add_u32_e32 v44, 28, v16
	v_add_u32_e32 v46, 30, v16
	v_ashrrev_i32_e32 v17, 31, v16
	v_add_u32_e32 v18, 2, v16
	v_add_u32_e32 v20, 4, v16
	v_add_u32_e32 v22, 6, v16
	v_add_u32_e32 v24, 8, v16
	v_add_u32_e32 v32, 16, v16
	v_add_u32_e32 v34, 18, v16
	v_add_u32_e32 v36, 20, v16
	v_add_u32_e32 v38, 22, v16
	v_add_u32_e32 v48, 32, v16
	v_add_u32_e32 v50, 34, v16
	v_add_u32_e32 v52, 36, v16
	v_add_u32_e32 v54, 38, v16
	v_add_u32_e32 v56, 40, v16
	v_add_u32_e32 v58, 42, v16
	v_add_u32_e32 v60, 44, v16
	v_add_u32_e32 v62, 46, v16
	v_add_u32_e32 v64, 48, v16
	v_add_u32_e32 v66, 50, v16
	v_add_u32_e32 v68, 52, v16
	v_add_u32_e32 v70, 54, v16
	v_add_u32_e32 v72, 56, v16
	v_add_u32_e32 v74, 58, v16
	v_add_u32_e32 v76, 60, v16
	v_add_u32_e32 v78, 62, v16
	s_ashr_i32 s13, s12, 31
	v_ashrrev_i32_e32 v27, 31, v26
	v_ashrrev_i32_e32 v29, 31, v28
	v_ashrrev_i32_e32 v31, 31, v30
	v_ashrrev_i32_e32 v41, 31, v40
	v_ashrrev_i32_e32 v43, 31, v42
	v_ashrrev_i32_e32 v45, 31, v44
	v_ashrrev_i32_e32 v47, 31, v46
	v_lshlrev_b64 v[16:17], 13, v[16:17]
	v_ashrrev_i32_e32 v19, 31, v18
	v_ashrrev_i32_e32 v21, 31, v20
	v_ashrrev_i32_e32 v23, 31, v22
	v_ashrrev_i32_e32 v25, 31, v24
	v_ashrrev_i32_e32 v33, 31, v32
	v_ashrrev_i32_e32 v35, 31, v34
	v_ashrrev_i32_e32 v37, 31, v36
	v_ashrrev_i32_e32 v39, 31, v38
	v_ashrrev_i32_e32 v49, 31, v48
	v_ashrrev_i32_e32 v51, 31, v50
	v_ashrrev_i32_e32 v53, 31, v52
	v_ashrrev_i32_e32 v55, 31, v54
	v_ashrrev_i32_e32 v57, 31, v56
	v_ashrrev_i32_e32 v59, 31, v58
	v_ashrrev_i32_e32 v61, 31, v60
	v_ashrrev_i32_e32 v63, 31, v62
	v_ashrrev_i32_e32 v65, 31, v64
	v_ashrrev_i32_e32 v67, 31, v66
	v_ashrrev_i32_e32 v69, 31, v68
	v_ashrrev_i32_e32 v71, 31, v70
	v_ashrrev_i32_e32 v73, 31, v72
	v_ashrrev_i32_e32 v75, 31, v74
	v_ashrrev_i32_e32 v77, 31, v76
	v_ashrrev_i32_e32 v79, 31, v78
	v_lshl_add_u64 v[80:81], s[12:13], 2, v[0:1]
	v_lshlrev_b64 v[26:27], 13, v[26:27]
	v_lshlrev_b64 v[28:29], 13, v[28:29]
	v_lshlrev_b64 v[30:31], 13, v[30:31]
	v_lshlrev_b64 v[40:41], 13, v[40:41]
	v_lshlrev_b64 v[42:43], 13, v[42:43]
	v_lshlrev_b64 v[44:45], 13, v[44:45]
	v_lshlrev_b64 v[46:47], 13, v[46:47]
	v_lshlrev_b64 v[18:19], 13, v[18:19]
	v_lshlrev_b64 v[20:21], 13, v[20:21]
	v_lshlrev_b64 v[22:23], 13, v[22:23]
	v_lshlrev_b64 v[24:25], 13, v[24:25]
	v_lshlrev_b64 v[32:33], 13, v[32:33]
	v_lshlrev_b64 v[34:35], 13, v[34:35]
	v_lshlrev_b64 v[36:37], 13, v[36:37]
	v_lshlrev_b64 v[38:39], 13, v[38:39]
	v_lshlrev_b64 v[48:49], 13, v[48:49]
	v_lshlrev_b64 v[50:51], 13, v[50:51]
	v_lshlrev_b64 v[52:53], 13, v[52:53]
	v_lshlrev_b64 v[54:55], 13, v[54:55]
	v_lshlrev_b64 v[56:57], 13, v[56:57]
	v_lshlrev_b64 v[58:59], 13, v[58:59]
	v_lshlrev_b64 v[60:61], 13, v[60:61]
	v_lshlrev_b64 v[62:63], 13, v[62:63]
	v_lshlrev_b64 v[64:65], 13, v[64:65]
	v_lshlrev_b64 v[66:67], 13, v[66:67]
	v_lshlrev_b64 v[68:69], 13, v[68:69]
	v_lshlrev_b64 v[70:71], 13, v[70:71]
	v_lshlrev_b64 v[72:73], 13, v[72:73]
	v_lshlrev_b64 v[74:75], 13, v[74:75]
	v_lshlrev_b64 v[76:77], 13, v[76:77]
	v_lshlrev_b64 v[78:79], 13, v[78:79]
	v_lshl_add_u64 v[16:17], v[80:81], 0, v[16:17]
	v_lshl_add_u64 v[26:27], v[80:81], 0, v[26:27]
	v_lshl_add_u64 v[28:29], v[80:81], 0, v[28:29]
	v_lshl_add_u64 v[30:31], v[80:81], 0, v[30:31]
	v_lshl_add_u64 v[40:41], v[80:81], 0, v[40:41]
	v_lshl_add_u64 v[42:43], v[80:81], 0, v[42:43]
	v_lshl_add_u64 v[44:45], v[80:81], 0, v[44:45]
	v_lshl_add_u64 v[46:47], v[80:81], 0, v[46:47]
	v_lshl_add_u64 v[18:19], v[80:81], 0, v[18:19]
	v_lshl_add_u64 v[20:21], v[80:81], 0, v[20:21]
	v_lshl_add_u64 v[22:23], v[80:81], 0, v[22:23]
	v_lshl_add_u64 v[24:25], v[80:81], 0, v[24:25]
	v_lshl_add_u64 v[32:33], v[80:81], 0, v[32:33]
	v_lshl_add_u64 v[34:35], v[80:81], 0, v[34:35]
	v_lshl_add_u64 v[36:37], v[80:81], 0, v[36:37]
	v_lshl_add_u64 v[38:39], v[80:81], 0, v[38:39]
	v_lshl_add_u64 v[48:49], v[80:81], 0, v[48:49]
	v_lshl_add_u64 v[50:51], v[80:81], 0, v[50:51]
	v_lshl_add_u64 v[52:53], v[80:81], 0, v[52:53]
	v_lshl_add_u64 v[54:55], v[80:81], 0, v[54:55]
	v_lshl_add_u64 v[56:57], v[80:81], 0, v[56:57]
	v_lshl_add_u64 v[58:59], v[80:81], 0, v[58:59]
	v_lshl_add_u64 v[60:61], v[80:81], 0, v[60:61]
	v_lshl_add_u64 v[62:63], v[80:81], 0, v[62:63]
	v_lshl_add_u64 v[64:65], v[80:81], 0, v[64:65]
	v_lshl_add_u64 v[66:67], v[80:81], 0, v[66:67]
	v_lshl_add_u64 v[68:69], v[80:81], 0, v[68:69]
	v_lshl_add_u64 v[70:71], v[80:81], 0, v[70:71]
	v_lshl_add_u64 v[72:73], v[80:81], 0, v[72:73]
	v_lshl_add_u64 v[74:75], v[80:81], 0, v[74:75]
	v_lshl_add_u64 v[76:77], v[80:81], 0, v[76:77]
	v_lshl_add_u64 v[78:79], v[80:81], 0, v[78:79]
	global_load_dword v80, v[16:17], off nt
	global_load_dword v81, v[18:19], off nt
	global_load_dword v82, v[20:21], off nt
	global_load_dword v83, v[22:23], off nt
	global_load_dword v84, v[24:25], off nt
	global_load_dword v85, v[26:27], off nt
	global_load_dword v86, v[28:29], off nt
	global_load_dword v87, v[30:31], off nt
	global_load_dword v88, v[32:33], off nt
	global_load_dword v89, v[34:35], off nt
	global_load_dword v90, v[36:37], off nt
	global_load_dword v91, v[38:39], off nt
	global_load_dword v92, v[40:41], off nt
	global_load_dword v93, v[42:43], off nt
	global_load_dword v94, v[44:45], off nt
	global_load_dword v26, v[46:47], off nt
	global_load_dword v27, v[48:49], off nt
	global_load_dword v28, v[50:51], off nt
	global_load_dword v29, v[52:53], off nt
	global_load_dword v30, v[54:55], off nt
	global_load_dword v31, v[56:57], off nt
	global_load_dword v40, v[58:59], off nt
	global_load_dword v41, v[60:61], off nt
	global_load_dword v42, v[62:63], off nt
	global_load_dword v43, v[64:65], off nt
	global_load_dword v44, v[66:67], off nt
	global_load_dword v45, v[68:69], off nt
	global_load_dword v95, v[70:71], off nt
	global_load_dword v96, v[72:73], off nt
	global_load_dword v97, v[74:75], off nt
	global_load_dword v46, v[76:77], off nt
	global_load_dword v47, v[78:79], off nt
	v_add_u32_e32 v18, s12, v6
	s_ashr_i32 s11, s10, 31
	v_ashrrev_i32_e32 v19, 31, v18
	v_add_u32_e32 v20, 8, v18
	v_add_u32_e32 v22, 16, v18
	v_add_u32_e32 v24, 24, v18
	v_lshl_add_u64 v[16:17], s[10:11], 1, v[2:3]
	v_lshlrev_b64 v[18:19], 11, v[18:19]
	v_ashrrev_i32_e32 v21, 31, v20
	v_ashrrev_i32_e32 v23, 31, v22
	v_ashrrev_i32_e32 v25, 31, v24
	s_waitcnt vmcnt(30)
; __device__ __forceinline__ unsigned cvt_pk_bf16(float lo, float hi) { const f32x2c v = {lo, hi}; const bf16x2c b = __builtin_convertvector(v, bf16x2c); return __builtin_bit_cast(unsigned, b); }
; #define LAS __attribute__((address_space(3)))
; template <int MODE> __device__ __forceinline__ void transpose_item(const float* W, int K, int N, bf16_t* WT, LAS float* scr, int item, int lane) {
;     ...
;     for (int i = 0; i < 32; ++i) scr[(2 * i + (lane >> 5)) * 33 + (lane & 31)] = tv[i];
;     asm volatile("s_waitcnt lgkmcnt(0)" ::: "memory");
;     const int c = lane & 7, dr0 = dest_row<MODE>(n0);
; #pragma unroll
;     for (int j = 0; j < 4; ++j) { const int n = (lane >> 3) + 8 * j; const LAS float* s = scr + (8 * c) * 33 + n;
;         u32x4 o; o.x = cvt_pk_bf16(s[0 * 33], s[1 * 33]); o.y = cvt_pk_bf16(s[2 * 33], s[3 * 33]); o.z = cvt_pk_bf16(s[4 * 33], s[5 * 33]); o.w = cvt_pk_bf16(s[6 * 33], s[7 * 33]);
;         *(u32x4*)(WT + (size_t)(dr0 + n) * K + k0 + 8 * c) = o; }
;     asm volatile("s_waitcnt lgkmcnt(0)" ::: "memory");
	ds_write2_b32 v8, v80, v81 offset1:66
	s_waitcnt vmcnt(28)
	ds_write2_b32 v8, v82, v83 offset0:132 offset1:198
	s_waitcnt vmcnt(26)
	ds_write2_b32 v9, v84, v85 offset0:8 offset1:74
	s_waitcnt vmcnt(24)
	ds_write2_b32 v9, v86, v87 offset0:140 offset1:206
	s_waitcnt vmcnt(22)
	ds_write2_b32 v10, v88, v89 offset0:16 offset1:82
	s_waitcnt vmcnt(20)
	ds_write2_b32 v10, v90, v91 offset0:148 offset1:214
	s_waitcnt vmcnt(18)
	ds_write2_b32 v11, v92, v93 offset0:24 offset1:90
	s_waitcnt vmcnt(16)
	ds_write2_b32 v11, v94, v26 offset0:156 offset1:222
	s_waitcnt vmcnt(14)
	ds_write2_b32 v12, v27, v28 offset0:32 offset1:98
	s_waitcnt vmcnt(12)
	ds_write2_b32 v12, v29, v30 offset0:164 offset1:230
	s_waitcnt vmcnt(10)
	ds_write2_b32 v13, v31, v40 offset0:40 offset1:106
	s_waitcnt vmcnt(8)
	ds_write2_b32 v13, v41, v42 offset0:172 offset1:238
	s_waitcnt vmcnt(6)
	ds_write2_b32 v14, v43, v44 offset0:48 offset1:114
	s_waitcnt vmcnt(4)
	ds_write2_b32 v14, v45, v95 offset0:180 offset1:246
	s_waitcnt vmcnt(2)
	ds_write2_b32 v15, v96, v97 offset0:56 offset1:122
	s_waitcnt vmcnt(0)
	ds_write2_b32 v15, v46, v47 offset0:188 offset1:254
	v_lshl_add_u64 v[32:33], v[16:17], 0, v[18:19]
	v_lshlrev_b64 v[18:19], 11, v[20:21]
	v_lshlrev_b64 v[20:21], 11, v[22:23]
	v_lshlrev_b64 v[22:23], 11, v[24:25]
	s_waitcnt lgkmcnt(0)
	v_lshl_add_u64 v[36:37], v[16:17], 0, v[20:21]
	v_lshl_add_u64 v[38:39], v[16:17], 0, v[22:23]
	ds_read2_b32 v[20:21], v7 offset0:33 offset1:41
	ds_read2_b32 v[22:23], v7 offset1:8
	ds_read2_b32 v[24:25], v7 offset0:66 offset1:74
	ds_read2_b32 v[26:27], v7 offset0:99 offset1:107
	ds_read2_b32 v[28:29], v7 offset0:132 offset1:140
	ds_read2_b32 v[30:31], v7 offset0:165 offset1:173
	ds_read2_b32 v[40:41], v7 offset0:198 offset1:206
	ds_read2_b32 v[42:43], v7 offset0:231 offset1:239
	ds_read2_b32 v[44:45], v7 offset0:49 offset1:57
	ds_read2_b32 v[46:47], v7 offset0:16 offset1:24
	ds_read2_b32 v[48:49], v7 offset0:82 offset1:90
	ds_read2_b32 v[50:51], v7 offset0:115 offset1:123
	ds_read2_b32 v[52:53], v7 offset0:148 offset1:156
	ds_read2_b32 v[54:55], v7 offset0:181 offset1:189
	ds_read2_b32 v[56:57], v7 offset0:214 offset1:222
	ds_read2_b32 v[58:59], v7 offset0:247 offset1:255
	v_lshl_add_u64 v[34:35], v[16:17], 0, v[18:19]
	s_waitcnt lgkmcnt(14)
	v_cvt_pk_bf16_f32 v16, v22, v20
	s_waitcnt lgkmcnt(12)
	v_cvt_pk_bf16_f32 v17, v24, v26
	s_waitcnt lgkmcnt(10)
	v_cvt_pk_bf16_f32 v18, v28, v30
	s_waitcnt lgkmcnt(8)
	v_cvt_pk_bf16_f32 v19, v40, v42
	v_cvt_pk_bf16_f32 v20, v23, v21
	v_cvt_pk_bf16_f32 v21, v25, v27
	v_cvt_pk_bf16_f32 v22, v29, v31
	v_cvt_pk_bf16_f32 v23, v41, v43
	s_waitcnt lgkmcnt(6)
	v_cvt_pk_bf16_f32 v24, v46, v44
	s_waitcnt lgkmcnt(4)
	v_cvt_pk_bf16_f32 v25, v48, v50
	s_waitcnt lgkmcnt(2)
	v_cvt_pk_bf16_f32 v26, v52, v54
	s_waitcnt lgkmcnt(0)
	v_cvt_pk_bf16_f32 v27, v56, v58
	v_cvt_pk_bf16_f32 v28, v47, v45
	v_cvt_pk_bf16_f32 v29, v49, v51
	v_cvt_pk_bf16_f32 v30, v53, v55
	v_cvt_pk_bf16_f32 v31, v57, v59
	global_store_dwordx4 v[32:33], v[16:19], off
	global_store_dwordx4 v[34:35], v[20:23], off
	global_store_dwordx4 v[36:37], v[24:27], off
	global_store_dwordx4 v[38:39], v[28:31], off
	s_waitcnt lgkmcnt(0)
	s_add_i32 s7, s7, s93
	s_add_i32 s3, s3, s6
	s_cmpk_lt_i32 s7, 0x400
	s_cbranch_scc1 .LBB0_48

; template <int MODE> __device__ __forceinline__ void transpose_item(const float* W, int K, int N, bf16_t* WT, LAS float* scr, int item, int lane) {
;     const int nblk = N / 32, kb = item / nblk, nb = item % nblk, k0 = 64 * kb, n0 = 32 * nb;
;     float tv[32];
; #pragma unroll
;     for (int i = 0; i < 32; ++i) tv[i] = W[(size_t)(k0 + 2 * i + (lane >> 5)) * N + n0 + (lane & 31)];
.LBB0_51:
	s_ashr_i32 s8, s7, 31
	s_lshr_b32 s8, s8, 26
	s_add_i32 s9, s7, s8
	s_and_b32 s8, s9, 0xffffffc0
	s_lshl_b32 s9, s9, 5
	s_and_b32 s9, s9, 0xfffff800
	v_add_u32_e32 v16, s8, v5
	s_sub_i32 s10, s3, s9
	v_add_u32_e32 v26, 10, v16
	v_add_u32_e32 v28, 12, v16
	v_add_u32_e32 v30, 14, v16
	v_add_u32_e32 v40, 24, v16
	v_add_u32_e32 v42, 26, v16
	v_add_u32_e32 v44, 28, v16
	v_add_u32_e32 v46, 30, v16
	v_ashrrev_i32_e32 v17, 31, v16
	v_add_u32_e32 v18, 2, v16
	v_add_u32_e32 v20, 4, v16
	v_add_u32_e32 v22, 6, v16
	v_add_u32_e32 v24, 8, v16
	v_add_u32_e32 v32, 16, v16
	v_add_u32_e32 v34, 18, v16
	v_add_u32_e32 v36, 20, v16
	v_add_u32_e32 v38, 22, v16
	v_add_u32_e32 v48, 32, v16
	v_add_u32_e32 v50, 34, v16
	v_add_u32_e32 v52, 36, v16
	v_add_u32_e32 v54, 38, v16
	v_add_u32_e32 v56, 40, v16
	v_add_u32_e32 v58, 42, v16
	v_add_u32_e32 v60, 44, v16
	v_add_u32_e32 v62, 46, v16
	v_add_u32_e32 v64, 48, v16
	v_add_u32_e32 v66, 50, v16
	v_add_u32_e32 v68, 52, v16
	v_add_u32_e32 v70, 54, v16
	v_add_u32_e32 v72, 56, v16
	v_add_u32_e32 v74, 58, v16
	v_add_u32_e32 v76, 60, v16
	v_add_u32_e32 v78, 62, v16
	s_ashr_i32 s11, s10, 31
	v_ashrrev_i32_e32 v27, 31, v26
	v_ashrrev_i32_e32 v29, 31, v28
	v_ashrrev_i32_e32 v31, 31, v30
	v_ashrrev_i32_e32 v41, 31, v40
	v_ashrrev_i32_e32 v43, 31, v42
	v_ashrrev_i32_e32 v45, 31, v44
	v_ashrrev_i32_e32 v47, 31, v46
	v_lshlrev_b64 v[16:17], 13, v[16:17]
	v_ashrrev_i32_e32 v19, 31, v18
	v_ashrrev_i32_e32 v21, 31, v20
	v_ashrrev_i32_e32 v23, 31, v22
	v_ashrrev_i32_e32 v25, 31, v24
	v_ashrrev_i32_e32 v33, 31, v32
	v_ashrrev_i32_e32 v35, 31, v34
	v_ashrrev_i32_e32 v37, 31, v36
	v_ashrrev_i32_e32 v39, 31, v38
	v_ashrrev_i32_e32 v49, 31, v48
	v_ashrrev_i32_e32 v51, 31, v50
	v_ashrrev_i32_e32 v53, 31, v52
	v_ashrrev_i32_e32 v55, 31, v54
	v_ashrrev_i32_e32 v57, 31, v56
	v_ashrrev_i32_e32 v59, 31, v58
	v_ashrrev_i32_e32 v61, 31, v60
	v_ashrrev_i32_e32 v63, 31, v62
	v_ashrrev_i32_e32 v65, 31, v64
	v_ashrrev_i32_e32 v67, 31, v66
	v_ashrrev_i32_e32 v69, 31, v68
	v_ashrrev_i32_e32 v71, 31, v70
	v_ashrrev_i32_e32 v73, 31, v72
	v_ashrrev_i32_e32 v75, 31, v74
	v_ashrrev_i32_e32 v77, 31, v76
	v_ashrrev_i32_e32 v79, 31, v78
	v_lshl_add_u64 v[80:81], s[10:11], 2, v[0:1]
	v_lshlrev_b64 v[26:27], 13, v[26:27]
	v_lshlrev_b64 v[28:29], 13, v[28:29]
	v_lshlrev_b64 v[30:31], 13, v[30:31]
	v_lshlrev_b64 v[40:41], 13, v[40:41]
	v_lshlrev_b64 v[42:43], 13, v[42:43]
	v_lshlrev_b64 v[44:45], 13, v[44:45]
	v_lshlrev_b64 v[46:47], 13, v[46:47]
	v_lshlrev_b64 v[18:19], 13, v[18:19]
	v_lshlrev_b64 v[20:21], 13, v[20:21]
	v_lshlrev_b64 v[22:23], 13, v[22:23]
	v_lshlrev_b64 v[24:25], 13, v[24:25]
	v_lshlrev_b64 v[32:33], 13, v[32:33]
	v_lshlrev_b64 v[34:35], 13, v[34:35]
	v_lshlrev_b64 v[36:37], 13, v[36:37]
	v_lshlrev_b64 v[38:39], 13, v[38:39]
	v_lshlrev_b64 v[48:49], 13, v[48:49]
	v_lshlrev_b64 v[50:51], 13, v[50:51]
	v_lshlrev_b64 v[52:53], 13, v[52:53]
	v_lshlrev_b64 v[54:55], 13, v[54:55]
	v_lshlrev_b64 v[56:57], 13, v[56:57]
	v_lshlrev_b64 v[58:59], 13, v[58:59]
	v_lshlrev_b64 v[60:61], 13, v[60:61]
	v_lshlrev_b64 v[62:63], 13, v[62:63]
	v_lshlrev_b64 v[64:65], 13, v[64:65]
	v_lshlrev_b64 v[66:67], 13, v[66:67]
	v_lshlrev_b64 v[68:69], 13, v[68:69]
	v_lshlrev_b64 v[70:71], 13, v[70:71]
	v_lshlrev_b64 v[72:73], 13, v[72:73]
	v_lshlrev_b64 v[74:75], 13, v[74:75]
	v_lshlrev_b64 v[76:77], 13, v[76:77]
	v_lshlrev_b64 v[78:79], 13, v[78:79]
	v_lshl_add_u64 v[16:17], v[80:81], 0, v[16:17]
	v_lshl_add_u64 v[26:27], v[80:81], 0, v[26:27]
	v_lshl_add_u64 v[28:29], v[80:81], 0, v[28:29]
	v_lshl_add_u64 v[30:31], v[80:81], 0, v[30:31]
	v_lshl_add_u64 v[40:41], v[80:81], 0, v[40:41]
	v_lshl_add_u64 v[42:43], v[80:81], 0, v[42:43]
	v_lshl_add_u64 v[44:45], v[80:81], 0, v[44:45]
	v_lshl_add_u64 v[46:47], v[80:81], 0, v[46:47]
	v_lshl_add_u64 v[18:19], v[80:81], 0, v[18:19]
	v_lshl_add_u64 v[20:21], v[80:81], 0, v[20:21]
	v_lshl_add_u64 v[22:23], v[80:81], 0, v[22:23]
	v_lshl_add_u64 v[24:25], v[80:81], 0, v[24:25]
	v_lshl_add_u64 v[32:33], v[80:81], 0, v[32:33]
	v_lshl_add_u64 v[34:35], v[80:81], 0, v[34:35]
	v_lshl_add_u64 v[36:37], v[80:81], 0, v[36:37]
	v_lshl_add_u64 v[38:39], v[80:81], 0, v[38:39]
	v_lshl_add_u64 v[48:49], v[80:81], 0, v[48:49]
	v_lshl_add_u64 v[50:51], v[80:81], 0, v[50:51]
	v_lshl_add_u64 v[52:53], v[80:81], 0, v[52:53]
	v_lshl_add_u64 v[54:55], v[80:81], 0, v[54:55]
	v_lshl_add_u64 v[56:57], v[80:81], 0, v[56:57]
	v_lshl_add_u64 v[58:59], v[80:81], 0, v[58:59]
	v_lshl_add_u64 v[60:61], v[80:81], 0, v[60:61]
	v_lshl_add_u64 v[62:63], v[80:81], 0, v[62:63]
	v_lshl_add_u64 v[64:65], v[80:81], 0, v[64:65]
	v_lshl_add_u64 v[66:67], v[80:81], 0, v[66:67]
	v_lshl_add_u64 v[68:69], v[80:81], 0, v[68:69]
	v_lshl_add_u64 v[70:71], v[80:81], 0, v[70:71]
	v_lshl_add_u64 v[72:73], v[80:81], 0, v[72:73]
	v_lshl_add_u64 v[74:75], v[80:81], 0, v[74:75]
	v_lshl_add_u64 v[76:77], v[80:81], 0, v[76:77]
	v_lshl_add_u64 v[78:79], v[80:81], 0, v[78:79]
	global_load_dword v80, v[16:17], off nt
	global_load_dword v81, v[18:19], off nt
	global_load_dword v82, v[20:21], off nt
	global_load_dword v83, v[22:23], off nt
	global_load_dword v84, v[24:25], off nt
	global_load_dword v85, v[26:27], off nt
	global_load_dword v86, v[28:29], off nt
	global_load_dword v87, v[30:31], off nt
	global_load_dword v88, v[32:33], off nt
	global_load_dword v89, v[34:35], off nt
	global_load_dword v90, v[36:37], off nt
	global_load_dword v91, v[38:39], off nt
	global_load_dword v92, v[40:41], off nt
	global_load_dword v93, v[42:43], off nt
	global_load_dword v94, v[44:45], off nt
	global_load_dword v26, v[46:47], off nt
	global_load_dword v27, v[48:49], off nt
	global_load_dword v28, v[50:51], off nt
	global_load_dword v29, v[52:53], off nt
	global_load_dword v30, v[54:55], off nt
	global_load_dword v31, v[56:57], off nt
	global_load_dword v40, v[58:59], off nt
	global_load_dword v41, v[60:61], off nt
	global_load_dword v42, v[62:63], off nt
	global_load_dword v43, v[64:65], off nt
	global_load_dword v44, v[66:67], off nt
	global_load_dword v45, v[68:69], off nt
	global_load_dword v95, v[70:71], off nt
	global_load_dword v96, v[72:73], off nt
	global_load_dword v97, v[74:75], off nt
	global_load_dword v46, v[76:77], off nt
	global_load_dword v47, v[78:79], off nt
	v_add_u32_e32 v18, s10, v6
	s_ashr_i32 s9, s8, 31
	v_ashrrev_i32_e32 v19, 31, v18
	v_add_u32_e32 v20, 8, v18
	v_add_u32_e32 v22, 16, v18
	v_add_u32_e32 v24, 24, v18
	v_lshl_add_u64 v[16:17], s[8:9], 1, v[2:3]
	v_lshlrev_b64 v[18:19], 11, v[18:19]
	v_ashrrev_i32_e32 v21, 31, v20
	v_ashrrev_i32_e32 v23, 31, v22
	v_ashrrev_i32_e32 v25, 31, v24
	s_waitcnt vmcnt(30)
; __device__ __forceinline__ unsigned cvt_pk_bf16(float lo, float hi) { const f32x2c v = {lo, hi}; const bf16x2c b = __builtin_convertvector(v, bf16x2c); return __builtin_bit_cast(unsigned, b); }
; #define LAS __attribute__((address_space(3)))
; template <int MODE> __device__ __forceinline__ void transpose_item(const float* W, int K, int N, bf16_t* WT, LAS float* scr, int item, int lane) {
;     ...
;     for (int i = 0; i < 32; ++i) scr[(2 * i + (lane >> 5)) * 33 + (lane & 31)] = tv[i];
;     asm volatile("s_waitcnt lgkmcnt(0)" ::: "memory");
;     const int c = lane & 7, dr0 = dest_row<MODE>(n0);
; #pragma unroll
;     for (int j = 0; j < 4; ++j) { const int n = (lane >> 3) + 8 * j; const LAS float* s = scr + (8 * c) * 33 + n;
;         u32x4 o; o.x = cvt_pk_bf16(s[0 * 33], s[1 * 33]); o.y = cvt_pk_bf16(s[2 * 33], s[3 * 33]); o.z = cvt_pk_bf16(s[4 * 33], s[5 * 33]); o.w = cvt_pk_bf16(s[6 * 33], s[7 * 33]);
;         *(u32x4*)(WT + (size_t)(dr0 + n) * K + k0 + 8 * c) = o; }
;     asm volatile("s_waitcnt lgkmcnt(0)" ::: "memory");
	ds_write2_b32 v8, v80, v81 offset1:66
	s_waitcnt vmcnt(28)
	ds_write2_b32 v8, v82, v83 offset0:132 offset1:198
	s_waitcnt vmcnt(26)
	ds_write2_b32 v9, v84, v85 offset0:8 offset1:74
	s_waitcnt vmcnt(24)
	ds_write2_b32 v9, v86, v87 offset0:140 offset1:206
	s_waitcnt vmcnt(22)
	ds_write2_b32 v10, v88, v89 offset0:16 offset1:82
	s_waitcnt vmcnt(20)
	ds_write2_b32 v10, v90, v91 offset0:148 offset1:214
	s_waitcnt vmcnt(18)
	ds_write2_b32 v11, v92, v93 offset0:24 offset1:90
	s_waitcnt vmcnt(16)
	ds_write2_b32 v11, v94, v26 offset0:156 offset1:222
	s_waitcnt vmcnt(14)
	ds_write2_b32 v12, v27, v28 offset0:32 offset1:98
	s_waitcnt vmcnt(12)
	ds_write2_b32 v12, v29, v30 offset0:164 offset1:230
	s_waitcnt vmcnt(10)
	ds_write2_b32 v13, v31, v40 offset0:40 offset1:106
	s_waitcnt vmcnt(8)
	ds_write2_b32 v13, v41, v42 offset0:172 offset1:238
	s_waitcnt vmcnt(6)
	ds_write2_b32 v14, v43, v44 offset0:48 offset1:114
	s_waitcnt vmcnt(4)
	ds_write2_b32 v14, v45, v95 offset0:180 offset1:246
	s_waitcnt vmcnt(2)
	ds_write2_b32 v15, v96, v97 offset0:56 offset1:122
	s_waitcnt vmcnt(0)
	ds_write2_b32 v15, v46, v47 offset0:188 offset1:254
	v_lshl_add_u64 v[32:33], v[16:17], 0, v[18:19]
	v_lshlrev_b64 v[18:19], 11, v[20:21]
	v_lshlrev_b64 v[20:21], 11, v[22:23]
	v_lshlrev_b64 v[22:23], 11, v[24:25]
	s_waitcnt lgkmcnt(0)
	v_lshl_add_u64 v[36:37], v[16:17], 0, v[20:21]
	v_lshl_add_u64 v[38:39], v[16:17], 0, v[22:23]
	ds_read2_b32 v[20:21], v7 offset0:33 offset1:41
	ds_read2_b32 v[22:23], v7 offset1:8
	ds_read2_b32 v[24:25], v7 offset0:66 offset1:74
	ds_read2_b32 v[26:27], v7 offset0:99 offset1:107
	ds_read2_b32 v[28:29], v7 offset0:132 offset1:140
	ds_read2_b32 v[30:31], v7 offset0:165 offset1:173
	ds_read2_b32 v[40:41], v7 offset0:198 offset1:206
	ds_read2_b32 v[42:43], v7 offset0:231 offset1:239
	ds_read2_b32 v[44:45], v7 offset0:49 offset1:57
	ds_read2_b32 v[46:47], v7 offset0:16 offset1:24
	ds_read2_b32 v[48:49], v7 offset0:82 offset1:90
	ds_read2_b32 v[50:51], v7 offset0:115 offset1:123
	ds_read2_b32 v[52:53], v7 offset0:148 offset1:156
	ds_read2_b32 v[54:55], v7 offset0:181 offset1:189
	ds_read2_b32 v[56:57], v7 offset0:214 offset1:222
	ds_read2_b32 v[58:59], v7 offset0:247 offset1:255
	v_lshl_add_u64 v[34:35], v[16:17], 0, v[18:19]
	s_waitcnt lgkmcnt(14)
	v_cvt_pk_bf16_f32 v16, v22, v20
	s_waitcnt lgkmcnt(12)
	v_cvt_pk_bf16_f32 v17, v24, v26
	s_waitcnt lgkmcnt(10)
	v_cvt_pk_bf16_f32 v18, v28, v30
	s_waitcnt lgkmcnt(8)
	v_cvt_pk_bf16_f32 v19, v40, v42
	v_cvt_pk_bf16_f32 v20, v23, v21
	v_cvt_pk_bf16_f32 v21, v25, v27
	v_cvt_pk_bf16_f32 v22, v29, v31
	v_cvt_pk_bf16_f32 v23, v41, v43
	s_waitcnt lgkmcnt(6)
	v_cvt_pk_bf16_f32 v24, v46, v44
	s_waitcnt lgkmcnt(4)
	v_cvt_pk_bf16_f32 v25, v48, v50
	s_waitcnt lgkmcnt(2)
	v_cvt_pk_bf16_f32 v26, v52, v54
	s_waitcnt lgkmcnt(0)
	v_cvt_pk_bf16_f32 v27, v56, v58
	v_cvt_pk_bf16_f32 v28, v47, v45
	v_cvt_pk_bf16_f32 v29, v49, v51
	v_cvt_pk_bf16_f32 v30, v53, v55
	v_cvt_pk_bf16_f32 v31, v57, v59
	global_store_dwordx4 v[32:33], v[16:19], off
	global_store_dwordx4 v[34:35], v[20:23], off
	global_store_dwordx4 v[36:37], v[24:27], off
	global_store_dwordx4 v[38:39], v[28:31], off
	s_waitcnt lgkmcnt(0)
	s_add_i32 s7, s7, s93
	s_add_i32 s3, s3, s6
	s_cmpk_lt_i32 s7, 0x400
	s_cbranch_scc1 .LBB0_51

; template <int MODE> __device__ __forceinline__ void transpose_item(const float* W, int K, int N, bf16_t* WT, LAS float* scr, int item, int lane) {
;     const int nblk = N / 32, kb = item / nblk, nb = item % nblk, k0 = 64 * kb, n0 = 32 * nb;
;     float tv[32];
; #pragma unroll
;     for (int i = 0; i < 32; ++i) tv[i] = W[(size_t)(k0 + 2 * i + (lane >> 5)) * N + n0 + (lane & 31)];
.LBB0_54:
	s_ashr_i32 s8, s7, 31
	s_lshr_b32 s8, s8, 26
	s_add_i32 s9, s7, s8
	s_and_b32 s8, s9, 0xffffffc0
	s_lshl_b32 s9, s9, 5
	s_and_b32 s9, s9, 0xfffff800
	v_add_u32_e32 v16, s8, v5
	s_sub_i32 s10, s3, s9
	v_add_u32_e32 v26, 10, v16
	v_add_u32_e32 v28, 12, v16
	v_add_u32_e32 v30, 14, v16
	v_add_u32_e32 v40, 24, v16
	v_add_u32_e32 v42, 26, v16
	v_add_u32_e32 v44, 28, v16
	v_add_u32_e32 v46, 30, v16
	v_ashrrev_i32_e32 v17, 31, v16
	v_add_u32_e32 v18, 2, v16
	v_add_u32_e32 v20, 4, v16
	v_add_u32_e32 v22, 6, v16
	v_add_u32_e32 v24, 8, v16
	v_add_u32_e32 v32, 16, v16
	v_add_u32_e32 v34, 18, v16
	v_add_u32_e32 v36, 20, v16
	v_add_u32_e32 v38, 22, v16
	v_add_u32_e32 v48, 32, v16
	v_add_u32_e32 v50, 34, v16
	v_add_u32_e32 v52, 36, v16
	v_add_u32_e32 v54, 38, v16
	v_add_u32_e32 v56, 40, v16
	v_add_u32_e32 v58, 42, v16
	v_add_u32_e32 v60, 44, v16
	v_add_u32_e32 v62, 46, v16
	v_add_u32_e32 v64, 48, v16
	v_add_u32_e32 v66, 50, v16
	v_add_u32_e32 v68, 52, v16
	v_add_u32_e32 v70, 54, v16
	v_add_u32_e32 v72, 56, v16
	v_add_u32_e32 v74, 58, v16
	v_add_u32_e32 v76, 60, v16
	v_add_u32_e32 v78, 62, v16
	s_ashr_i32 s11, s10, 31
	v_ashrrev_i32_e32 v27, 31, v26
	v_ashrrev_i32_e32 v29, 31, v28
	v_ashrrev_i32_e32 v31, 31, v30
	v_ashrrev_i32_e32 v41, 31, v40
	v_ashrrev_i32_e32 v43, 31, v42
	v_ashrrev_i32_e32 v45, 31, v44
	v_ashrrev_i32_e32 v47, 31, v46
	v_lshlrev_b64 v[16:17], 13, v[16:17]
	v_ashrrev_i32_e32 v19, 31, v18
	v_ashrrev_i32_e32 v21, 31, v20
	v_ashrrev_i32_e32 v23, 31, v22
	v_ashrrev_i32_e32 v25, 31, v24
	v_ashrrev_i32_e32 v33, 31, v32
	v_ashrrev_i32_e32 v35, 31, v34
	v_ashrrev_i32_e32 v37, 31, v36
	v_ashrrev_i32_e32 v39, 31, v38
	v_ashrrev_i32_e32 v49, 31, v48
	v_ashrrev_i32_e32 v51, 31, v50
	v_ashrrev_i32_e32 v53, 31, v52
	v_ashrrev_i32_e32 v55, 31, v54
	v_ashrrev_i32_e32 v57, 31, v56
	v_ashrrev_i32_e32 v59, 31, v58
	v_ashrrev_i32_e32 v61, 31, v60
	v_ashrrev_i32_e32 v63, 31, v62
	v_ashrrev_i32_e32 v65, 31, v64
	v_ashrrev_i32_e32 v67, 31, v66
	v_ashrrev_i32_e32 v69, 31, v68
	v_ashrrev_i32_e32 v71, 31, v70
	v_ashrrev_i32_e32 v73, 31, v72
	v_ashrrev_i32_e32 v75, 31, v74
	v_ashrrev_i32_e32 v77, 31, v76
	v_ashrrev_i32_e32 v79, 31, v78
	v_lshl_add_u64 v[80:81], s[10:11], 2, v[0:1]
	v_lshlrev_b64 v[26:27], 13, v[26:27]
	v_lshlrev_b64 v[28:29], 13, v[28:29]
	v_lshlrev_b64 v[30:31], 13, v[30:31]
	v_lshlrev_b64 v[40:41], 13, v[40:41]
	v_lshlrev_b64 v[42:43], 13, v[42:43]
	v_lshlrev_b64 v[44:45], 13, v[44:45]
	v_lshlrev_b64 v[46:47], 13, v[46:47]
	v_lshlrev_b64 v[18:19], 13, v[18:19]
	v_lshlrev_b64 v[20:21], 13, v[20:21]
	v_lshlrev_b64 v[22:23], 13, v[22:23]
	v_lshlrev_b64 v[24:25], 13, v[24:25]
	v_lshlrev_b64 v[32:33], 13, v[32:33]
	v_lshlrev_b64 v[34:35], 13, v[34:35]
	v_lshlrev_b64 v[36:37], 13, v[36:37]
	v_lshlrev_b64 v[38:39], 13, v[38:39]
	v_lshlrev_b64 v[48:49], 13, v[48:49]
	v_lshlrev_b64 v[50:51], 13, v[50:51]
	v_lshlrev_b64 v[52:53], 13, v[52:53]
	v_lshlrev_b64 v[54:55], 13, v[54:55]
	v_lshlrev_b64 v[56:57], 13, v[56:57]
	v_lshlrev_b64 v[58:59], 13, v[58:59]
	v_lshlrev_b64 v[60:61], 13, v[60:61]
	v_lshlrev_b64 v[62:63], 13, v[62:63]
	v_lshlrev_b64 v[64:65], 13, v[64:65]
	v_lshlrev_b64 v[66:67], 13, v[66:67]
	v_lshlrev_b64 v[68:69], 13, v[68:69]
	v_lshlrev_b64 v[70:71], 13, v[70:71]
	v_lshlrev_b64 v[72:73], 13, v[72:73]
	v_lshlrev_b64 v[74:75], 13, v[74:75]
	v_lshlrev_b64 v[76:77], 13, v[76:77]
	v_lshlrev_b64 v[78:79], 13, v[78:79]
	v_lshl_add_u64 v[16:17], v[80:81], 0, v[16:17]
	v_lshl_add_u64 v[26:27], v[80:81], 0, v[26:27]
	v_lshl_add_u64 v[28:29], v[80:81], 0, v[28:29]
	v_lshl_add_u64 v[30:31], v[80:81], 0, v[30:31]
	v_lshl_add_u64 v[40:41], v[80:81], 0, v[40:41]
	v_lshl_add_u64 v[42:43], v[80:81], 0, v[42:43]
	v_lshl_add_u64 v[44:45], v[80:81], 0, v[44:45]
	v_lshl_add_u64 v[46:47], v[80:81], 0, v[46:47]
	v_lshl_add_u64 v[18:19], v[80:81], 0, v[18:19]
	v_lshl_add_u64 v[20:21], v[80:81], 0, v[20:21]
	v_lshl_add_u64 v[22:23], v[80:81], 0, v[22:23]
	v_lshl_add_u64 v[24:25], v[80:81], 0, v[24:25]
	v_lshl_add_u64 v[32:33], v[80:81], 0, v[32:33]
	v_lshl_add_u64 v[34:35], v[80:81], 0, v[34:35]
	v_lshl_add_u64 v[36:37], v[80:81], 0, v[36:37]
	v_lshl_add_u64 v[38:39], v[80:81], 0, v[38:39]
	v_lshl_add_u64 v[48:49], v[80:81], 0, v[48:49]
	v_lshl_add_u64 v[50:51], v[80:81], 0, v[50:51]
	v_lshl_add_u64 v[52:53], v[80:81], 0, v[52:53]
	v_lshl_add_u64 v[54:55], v[80:81], 0, v[54:55]
	v_lshl_add_u64 v[56:57], v[80:81], 0, v[56:57]
	v_lshl_add_u64 v[58:59], v[80:81], 0, v[58:59]
	v_lshl_add_u64 v[60:61], v[80:81], 0, v[60:61]
	v_lshl_add_u64 v[62:63], v[80:81], 0, v[62:63]
	v_lshl_add_u64 v[64:65], v[80:81], 0, v[64:65]
	v_lshl_add_u64 v[66:67], v[80:81], 0, v[66:67]
	v_lshl_add_u64 v[68:69], v[80:81], 0, v[68:69]
	v_lshl_add_u64 v[70:71], v[80:81], 0, v[70:71]
	v_lshl_add_u64 v[72:73], v[80:81], 0, v[72:73]
	v_lshl_add_u64 v[74:75], v[80:81], 0, v[74:75]
	v_lshl_add_u64 v[76:77], v[80:81], 0, v[76:77]
	v_lshl_add_u64 v[78:79], v[80:81], 0, v[78:79]
	global_load_dword v80, v[16:17], off nt
	global_load_dword v81, v[18:19], off nt
	global_load_dword v82, v[20:21], off nt
	global_load_dword v83, v[22:23], off nt
	global_load_dword v84, v[24:25], off nt
	global_load_dword v85, v[26:27], off nt
	global_load_dword v86, v[28:29], off nt
	global_load_dword v87, v[30:31], off nt
	global_load_dword v88, v[32:33], off nt
	global_load_dword v89, v[34:35], off nt
	global_load_dword v90, v[36:37], off nt
	global_load_dword v91, v[38:39], off nt
	global_load_dword v92, v[40:41], off nt
	global_load_dword v93, v[42:43], off nt
	global_load_dword v94, v[44:45], off nt
	global_load_dword v26, v[46:47], off nt
	global_load_dword v27, v[48:49], off nt
	global_load_dword v28, v[50:51], off nt
	global_load_dword v29, v[52:53], off nt
	global_load_dword v30, v[54:55], off nt
	global_load_dword v31, v[56:57], off nt
	global_load_dword v40, v[58:59], off nt
	global_load_dword v41, v[60:61], off nt
	global_load_dword v42, v[62:63], off nt
	global_load_dword v43, v[64:65], off nt
	global_load_dword v44, v[66:67], off nt
	global_load_dword v45, v[68:69], off nt
	global_load_dword v95, v[70:71], off nt
	global_load_dword v96, v[72:73], off nt
	global_load_dword v97, v[74:75], off nt
	global_load_dword v46, v[76:77], off nt
	global_load_dword v47, v[78:79], off nt
	v_add_u32_e32 v18, s10, v6
	s_ashr_i32 s9, s8, 31
	v_ashrrev_i32_e32 v19, 31, v18
	v_add_u32_e32 v20, 8, v18
	v_add_u32_e32 v22, 16, v18
	v_add_u32_e32 v24, 24, v18
	v_lshl_add_u64 v[16:17], s[8:9], 1, v[2:3]
	v_lshlrev_b64 v[18:19], 12, v[18:19]
	v_ashrrev_i32_e32 v21, 31, v20
	v_ashrrev_i32_e32 v23, 31, v22
	v_ashrrev_i32_e32 v25, 31, v24
	s_waitcnt vmcnt(30)
; __device__ __forceinline__ unsigned cvt_pk_bf16(float lo, float hi) { const f32x2c v = {lo, hi}; const bf16x2c b = __builtin_convertvector(v, bf16x2c); return __builtin_bit_cast(unsigned, b); }
; #define LAS __attribute__((address_space(3)))
; template <int MODE> __device__ __forceinline__ void transpose_item(const float* W, int K, int N, bf16_t* WT, LAS float* scr, int item, int lane) {
;     ...
;     for (int i = 0; i < 32; ++i) scr[(2 * i + (lane >> 5)) * 33 + (lane & 31)] = tv[i];
;     asm volatile("s_waitcnt lgkmcnt(0)" ::: "memory");
;     const int c = lane & 7, dr0 = dest_row<MODE>(n0);
; #pragma unroll
;     for (int j = 0; j < 4; ++j) { const int n = (lane >> 3) + 8 * j; const LAS float* s = scr + (8 * c) * 33 + n;
;         u32x4 o; o.x = cvt_pk_bf16(s[0 * 33], s[1 * 33]); o.y = cvt_pk_bf16(s[2 * 33], s[3 * 33]); o.z = cvt_pk_bf16(s[4 * 33], s[5 * 33]); o.w = cvt_pk_bf16(s[6 * 33], s[7 * 33]);
;         *(u32x4*)(WT + (size_t)(dr0 + n) * K + k0 + 8 * c) = o; }
;     asm volatile("s_waitcnt lgkmcnt(0)" ::: "memory");
	ds_write2_b32 v8, v80, v81 offset1:66
	s_waitcnt vmcnt(28)
	ds_write2_b32 v8, v82, v83 offset0:132 offset1:198
	s_waitcnt vmcnt(26)
	ds_write2_b32 v9, v84, v85 offset0:8 offset1:74
	s_waitcnt vmcnt(24)
	ds_write2_b32 v9, v86, v87 offset0:140 offset1:206
	s_waitcnt vmcnt(22)
	ds_write2_b32 v10, v88, v89 offset0:16 offset1:82
	s_waitcnt vmcnt(20)
	ds_write2_b32 v10, v90, v91 offset0:148 offset1:214
	s_waitcnt vmcnt(18)
	ds_write2_b32 v11, v92, v93 offset0:24 offset1:90
	s_waitcnt vmcnt(16)
	ds_write2_b32 v11, v94, v26 offset0:156 offset1:222
	s_waitcnt vmcnt(14)
	ds_write2_b32 v12, v27, v28 offset0:32 offset1:98
	s_waitcnt vmcnt(12)
	ds_write2_b32 v12, v29, v30 offset0:164 offset1:230
	s_waitcnt vmcnt(10)
	ds_write2_b32 v13, v31, v40 offset0:40 offset1:106
	s_waitcnt vmcnt(8)
	ds_write2_b32 v13, v41, v42 offset0:172 offset1:238
	s_waitcnt vmcnt(6)
	ds_write2_b32 v14, v43, v44 offset0:48 offset1:114
	s_waitcnt vmcnt(4)
	ds_write2_b32 v14, v45, v95 offset0:180 offset1:246
	s_waitcnt vmcnt(2)
	ds_write2_b32 v15, v96, v97 offset0:56 offset1:122
	s_waitcnt vmcnt(0)
	ds_write2_b32 v15, v46, v47 offset0:188 offset1:254
	v_lshl_add_u64 v[32:33], v[16:17], 0, v[18:19]
	v_lshlrev_b64 v[18:19], 12, v[20:21]
	v_lshlrev_b64 v[20:21], 12, v[22:23]
	v_lshlrev_b64 v[22:23], 12, v[24:25]
	s_waitcnt lgkmcnt(0)
	v_lshl_add_u64 v[36:37], v[16:17], 0, v[20:21]
	v_lshl_add_u64 v[38:39], v[16:17], 0, v[22:23]
	ds_read2_b32 v[20:21], v7 offset0:33 offset1:41
	ds_read2_b32 v[22:23], v7 offset1:8
	ds_read2_b32 v[24:25], v7 offset0:66 offset1:74
	ds_read2_b32 v[26:27], v7 offset0:99 offset1:107
	ds_read2_b32 v[28:29], v7 offset0:132 offset1:140
	ds_read2_b32 v[30:31], v7 offset0:165 offset1:173
	ds_read2_b32 v[40:41], v7 offset0:198 offset1:206
	ds_read2_b32 v[42:43], v7 offset0:231 offset1:239
	ds_read2_b32 v[44:45], v7 offset0:49 offset1:57
	ds_read2_b32 v[46:47], v7 offset0:16 offset1:24
	ds_read2_b32 v[48:49], v7 offset0:82 offset1:90
	ds_read2_b32 v[50:51], v7 offset0:115 offset1:123
	ds_read2_b32 v[52:53], v7 offset0:148 offset1:156
	ds_read2_b32 v[54:55], v7 offset0:181 offset1:189
	ds_read2_b32 v[56:57], v7 offset0:214 offset1:222
	ds_read2_b32 v[58:59], v7 offset0:247 offset1:255
	v_lshl_add_u64 v[34:35], v[16:17], 0, v[18:19]
	s_waitcnt lgkmcnt(14)
	v_cvt_pk_bf16_f32 v16, v22, v20
	s_waitcnt lgkmcnt(12)
	v_cvt_pk_bf16_f32 v17, v24, v26
	s_waitcnt lgkmcnt(10)
	v_cvt_pk_bf16_f32 v18, v28, v30
	s_waitcnt lgkmcnt(8)
	v_cvt_pk_bf16_f32 v19, v40, v42
	v_cvt_pk_bf16_f32 v20, v23, v21
	v_cvt_pk_bf16_f32 v21, v25, v27
	v_cvt_pk_bf16_f32 v22, v29, v31
	v_cvt_pk_bf16_f32 v23, v41, v43
	s_waitcnt lgkmcnt(6)
	v_cvt_pk_bf16_f32 v24, v46, v44
	s_waitcnt lgkmcnt(4)
	v_cvt_pk_bf16_f32 v25, v48, v50
	s_waitcnt lgkmcnt(2)
	v_cvt_pk_bf16_f32 v26, v52, v54
	s_waitcnt lgkmcnt(0)
	v_cvt_pk_bf16_f32 v27, v56, v58
	v_cvt_pk_bf16_f32 v28, v47, v45
	v_cvt_pk_bf16_f32 v29, v49, v51
	v_cvt_pk_bf16_f32 v30, v53, v55
	v_cvt_pk_bf16_f32 v31, v57, v59
	global_store_dwordx4 v[32:33], v[16:19], off
	global_store_dwordx4 v[34:35], v[20:23], off
	global_store_dwordx4 v[36:37], v[24:27], off
	global_store_dwordx4 v[38:39], v[28:31], off
	s_waitcnt lgkmcnt(0)
	s_add_i32 s7, s7, s93
	s_add_i32 s3, s3, s6
	s_cmpk_lt_i32 s7, 0x800
	s_cbranch_scc1 .LBB0_54

; __device__ __forceinline__ unsigned cvt_pk_bf16(float lo, float hi) { const f32x2c v = {lo, hi}; const bf16x2c b = __builtin_convertvector(v, bf16x2c); return __builtin_bit_cast(unsigned, b); }
; #define LAS __attribute__((address_space(3)))
; template <int MODE> __device__ __forceinline__ void transpose_item(const float* W, int K, int N, bf16_t* WT, LAS float* scr, int item, int lane) {
;     const int nblk = N / 32, kb = item / nblk, nb = item % nblk, k0 = 64 * kb, n0 = 32 * nb;
;     float tv[32];
; #pragma unroll
;     for (int i = 0; i < 32; ++i) tv[i] = W[(size_t)(k0 + 2 * i + (lane >> 5)) * N + n0 + (lane & 31)];
; #pragma unroll
;     for (int i = 0; i < 32; ++i) scr[(2 * i + (lane >> 5)) * 33 + (lane & 31)] = tv[i];
;     asm volatile("s_waitcnt lgkmcnt(0)" ::: "memory");
;     const int c = lane & 7, dr0 = dest_row<MODE>(n0);
; #pragma unroll
;     for (int j = 0; j < 4; ++j) { const int n = (lane >> 3) + 8 * j; const LAS float* s = scr + (8 * c) * 33 + n;
;         u32x4 o; o.x = cvt_pk_bf16(s[0 * 33], s[1 * 33]); o.y = cvt_pk_bf16(s[2 * 33], s[3 * 33]); o.z = cvt_pk_bf16(s[4 * 33], s[5 * 33]); o.w = cvt_pk_bf16(s[6 * 33], s[7 * 33]);
;         *(u32x4*)(WT + (size_t)(dr0 + n) * K + k0 + 8 * c) = o; }
;     asm volatile("s_waitcnt lgkmcnt(0)" ::: "memory");
; }
.LBB0_713:
	s_mul_hi_i32 s6, s22, 0x2e8ba2e9
	s_lshr_b32 s7, s6, 31
	s_ashr_i32 s6, s6, 6
	s_add_i32 s7, s6, s7
	s_mul_i32 s10, s7, 0xffffd400
	s_add_i32 s10, s3, s10
	s_lshl_b32 s6, s7, 6
	s_ashr_i32 s11, s10, 31
	v_add_u32_e32 v15, s6, v4
	v_lshl_add_u64 v[16:17], s[10:11], 2, v[0:1]
	v_mad_i64_i32 v[18:19], s[12:13], v15, s15, v[16:17]
	v_add_u32_e32 v20, 2, v15
	v_add_u32_e32 v22, 4, v15
	v_add_u32_e32 v24, 6, v15
	v_add_u32_e32 v26, 8, v15
	v_add_u32_e32 v28, 10, v15
	v_add_u32_e32 v30, 12, v15
	v_add_u32_e32 v32, 14, v15
	v_mad_i64_i32 v[20:21], s[12:13], v20, s15, v[16:17]
	v_mad_i64_i32 v[22:23], s[12:13], v22, s15, v[16:17]
	v_mad_i64_i32 v[24:25], s[12:13], v24, s15, v[16:17]
	v_mad_i64_i32 v[26:27], s[12:13], v26, s15, v[16:17]
	v_mad_i64_i32 v[28:29], s[12:13], v28, s15, v[16:17]
	v_mad_i64_i32 v[30:31], s[12:13], v30, s15, v[16:17]
	v_mad_i64_i32 v[32:33], s[12:13], v32, s15, v[16:17]
	global_load_dword v34, v[18:19], off nt
	global_load_dword v35, v[20:21], off nt
	global_load_dword v36, v[22:23], off nt
	global_load_dword v37, v[24:25], off nt
	global_load_dword v38, v[26:27], off nt
	global_load_dword v39, v[28:29], off nt
	global_load_dword v40, v[30:31], off nt
	global_load_dword v41, v[32:33], off nt
	v_add_u32_e32 v18, 16, v15
	v_mad_i64_i32 v[18:19], s[12:13], v18, s15, v[16:17]
	v_add_u32_e32 v20, 18, v15
	v_add_u32_e32 v22, 20, v15
	v_add_u32_e32 v24, 22, v15
	v_add_u32_e32 v26, 24, v15
	v_add_u32_e32 v28, 26, v15
	v_add_u32_e32 v30, 28, v15
	v_add_u32_e32 v32, 30, v15
	v_mad_i64_i32 v[20:21], s[12:13], v20, s15, v[16:17]
	v_mad_i64_i32 v[22:23], s[12:13], v22, s15, v[16:17]
	v_mad_i64_i32 v[24:25], s[12:13], v24, s15, v[16:17]
	v_mad_i64_i32 v[26:27], s[12:13], v26, s15, v[16:17]
	v_mad_i64_i32 v[28:29], s[12:13], v28, s15, v[16:17]
	v_mad_i64_i32 v[30:31], s[12:13], v30, s15, v[16:17]
	v_mad_i64_i32 v[32:33], s[12:13], v32, s15, v[16:17]
	global_load_dword v42, v[18:19], off nt
	global_load_dword v43, v[20:21], off nt
	global_load_dword v44, v[22:23], off nt
	global_load_dword v45, v[24:25], off nt
	global_load_dword v46, v[26:27], off nt
	global_load_dword v47, v[28:29], off nt
	global_load_dword v48, v[30:31], off nt
	global_load_dword v49, v[32:33], off nt
	v_add_u32_e32 v18, 32, v15
	v_mad_i64_i32 v[18:19], s[12:13], v18, s15, v[16:17]
	v_add_u32_e32 v20, 34, v15
	v_add_u32_e32 v22, 36, v15
	v_add_u32_e32 v24, 38, v15
	v_add_u32_e32 v26, 40, v15
	v_add_u32_e32 v28, 42, v15
	v_add_u32_e32 v30, 44, v15
	v_add_u32_e32 v32, 46, v15
	v_mad_i64_i32 v[20:21], s[12:13], v20, s15, v[16:17]
	v_mad_i64_i32 v[22:23], s[12:13], v22, s15, v[16:17]
	v_mad_i64_i32 v[24:25], s[12:13], v24, s15, v[16:17]
	v_mad_i64_i32 v[26:27], s[12:13], v26, s15, v[16:17]
	v_mad_i64_i32 v[28:29], s[12:13], v28, s15, v[16:17]
	v_mad_i64_i32 v[30:31], s[12:13], v30, s15, v[16:17]
	v_mad_i64_i32 v[32:33], s[12:13], v32, s15, v[16:17]
	global_load_dword v50, v[18:19], off nt
	global_load_dword v51, v[20:21], off nt
	global_load_dword v52, v[22:23], off nt
	global_load_dword v53, v[24:25], off nt
	global_load_dword v54, v[26:27], off nt
	global_load_dword v55, v[28:29], off nt
	global_load_dword v56, v[30:31], off nt
	global_load_dword v57, v[32:33], off nt
	v_add_u32_e32 v18, 48, v15
	v_mad_i64_i32 v[18:19], s[12:13], v18, s15, v[16:17]
	v_add_u32_e32 v20, 50, v15
	v_add_u32_e32 v22, 52, v15
	v_add_u32_e32 v24, 54, v15
	v_add_u32_e32 v26, 56, v15
	v_add_u32_e32 v28, 58, v15
	v_add_u32_e32 v30, 60, v15
	v_add_u32_e32 v15, 62, v15
	v_mad_i64_i32 v[20:21], s[12:13], v20, s15, v[16:17]
	v_mad_i64_i32 v[22:23], s[12:13], v22, s15, v[16:17]
	v_mad_i64_i32 v[24:25], s[12:13], v24, s15, v[16:17]
	v_mad_i64_i32 v[26:27], s[12:13], v26, s15, v[16:17]
	v_mad_i64_i32 v[28:29], s[12:13], v28, s15, v[16:17]
	v_mad_i64_i32 v[30:31], s[12:13], v30, s15, v[16:17]
	v_mad_i64_i32 v[16:17], s[12:13], v15, s15, v[16:17]
	global_load_dword v15, v[18:19], off nt
	global_load_dword v32, v[20:21], off nt
	global_load_dword v33, v[22:23], off nt
	global_load_dword v58, v[24:25], off nt
	global_load_dword v59, v[26:27], off nt
	global_load_dword v60, v[28:29], off nt
	global_load_dword v61, v[30:31], off nt
	global_load_dword v62, v[16:17], off nt
	s_waitcnt vmcnt(30)
	ds_write2_b32 v7, v34, v35 offset1:66
	s_waitcnt vmcnt(28)
	ds_write2_b32 v7, v36, v37 offset0:132 offset1:198
	s_waitcnt vmcnt(26)
	ds_write2_b32 v8, v38, v39 offset0:8 offset1:74
	s_waitcnt vmcnt(24)
	ds_write2_b32 v8, v40, v41 offset0:140 offset1:206
	s_waitcnt vmcnt(22)
	ds_write2_b32 v9, v42, v43 offset0:16 offset1:82
	s_waitcnt vmcnt(20)
	ds_write2_b32 v9, v44, v45 offset0:148 offset1:214
	s_waitcnt vmcnt(18)
	ds_write2_b32 v10, v46, v47 offset0:24 offset1:90
	s_waitcnt vmcnt(16)
	ds_write2_b32 v10, v48, v49 offset0:156 offset1:222
	s_waitcnt vmcnt(14)
	ds_write2_b32 v11, v50, v51 offset0:32 offset1:98
	s_waitcnt vmcnt(12)
	ds_write2_b32 v11, v52, v53 offset0:164 offset1:230
	s_waitcnt vmcnt(10)
	ds_write2_b32 v12, v54, v55 offset0:40 offset1:106
	s_waitcnt vmcnt(8)
	ds_write2_b32 v12, v56, v57 offset0:172 offset1:238
	s_waitcnt vmcnt(6)
	ds_write2_b32 v13, v15, v32 offset0:48 offset1:114
	s_waitcnt vmcnt(4)
	ds_write2_b32 v13, v33, v58 offset0:180 offset1:246
	s_waitcnt vmcnt(2)
	ds_write2_b32 v14, v59, v60 offset0:56 offset1:122
	s_waitcnt vmcnt(0)
	ds_write2_b32 v14, v61, v62 offset0:188 offset1:254
	s_mul_i32 s11, s7, 0xfffffea0
	s_waitcnt lgkmcnt(0)
	s_add_i32 s11, s22, s11
	s_cmpk_gt_i32 s11, 0xaf
	s_mov_b64 s[12:13], -1
	s_cbranch_scc0 .LBB0_715
	s_mul_i32 s11, s7, 0xffffa800
	s_add_i32 s11, s9, s11
	s_and_b32 s11, s11, 0x7fffff00
	s_and_b32 s12, s10, 0x60
	s_or_b32 s11, s12, s11
	s_bitset1_b32 s11, 7
	s_mov_b64 s[12:13], 0

; template <int MODE> __device__ __forceinline__ void transpose_item(const float* W, int K, int N, bf16_t* WT, LAS float* scr, int item, int lane) {
;     const int nblk = N / 32, kb = item / nblk, nb = item % nblk, k0 = 64 * kb, n0 = 32 * nb;
;     float tv[32];
; #pragma unroll
;     for (int i = 0; i < 32; ++i) tv[i] = W[(size_t)(k0 + 2 * i + (lane >> 5)) * N + n0 + (lane & 31)];
.LBB0_719:
	s_ashr_i32 s6, s92, 31
	s_lshr_b32 s6, s6, 26
	s_add_i32 s7, s92, s6
	s_and_b32 s6, s7, 0xffffffc0
	s_lshl_b32 s7, s7, 5
	s_and_b32 s7, s7, 0xfffff800
	v_add_u32_e32 v16, s6, v4
	s_sub_i32 s10, s3, s7
	v_add_u32_e32 v18, 2, v16
	v_add_u32_e32 v20, 4, v16
	v_add_u32_e32 v22, 6, v16
	v_add_u32_e32 v24, 8, v16
	v_add_u32_e32 v26, 10, v16
	v_add_u32_e32 v28, 12, v16
	v_add_u32_e32 v30, 14, v16
	v_add_u32_e32 v40, 24, v16
	v_add_u32_e32 v42, 26, v16
	v_ashrrev_i32_e32 v17, 31, v16
	v_add_u32_e32 v32, 16, v16
	v_add_u32_e32 v34, 18, v16
	v_add_u32_e32 v36, 20, v16
	v_add_u32_e32 v38, 22, v16
	v_add_u32_e32 v44, 28, v16
	v_add_u32_e32 v46, 30, v16
	v_add_u32_e32 v48, 32, v16
	v_add_u32_e32 v50, 34, v16
	v_add_u32_e32 v52, 36, v16
	v_add_u32_e32 v54, 38, v16
	v_add_u32_e32 v56, 40, v16
	v_add_u32_e32 v58, 42, v16
	v_add_u32_e32 v60, 44, v16
	v_add_u32_e32 v62, 46, v16
	v_add_u32_e32 v64, 48, v16
	v_add_u32_e32 v66, 50, v16
	v_add_u32_e32 v68, 52, v16
	v_add_u32_e32 v70, 54, v16
	v_add_u32_e32 v72, 56, v16
	v_add_u32_e32 v74, 58, v16
	v_add_u32_e32 v76, 60, v16
	v_add_u32_e32 v78, 62, v16
	s_ashr_i32 s11, s10, 31
	v_ashrrev_i32_e32 v19, 31, v18
	v_ashrrev_i32_e32 v21, 31, v20
	v_ashrrev_i32_e32 v23, 31, v22
	v_ashrrev_i32_e32 v25, 31, v24
	v_ashrrev_i32_e32 v27, 31, v26
	v_ashrrev_i32_e32 v29, 31, v28
	v_ashrrev_i32_e32 v31, 31, v30
	v_ashrrev_i32_e32 v41, 31, v40
	v_ashrrev_i32_e32 v43, 31, v42
	v_lshlrev_b64 v[16:17], 13, v[16:17]
	v_ashrrev_i32_e32 v33, 31, v32
	v_ashrrev_i32_e32 v35, 31, v34
	v_ashrrev_i32_e32 v37, 31, v36
	v_ashrrev_i32_e32 v39, 31, v38
	v_ashrrev_i32_e32 v45, 31, v44
	v_ashrrev_i32_e32 v47, 31, v46
	v_ashrrev_i32_e32 v49, 31, v48
	v_ashrrev_i32_e32 v51, 31, v50
	v_ashrrev_i32_e32 v53, 31, v52
	v_ashrrev_i32_e32 v55, 31, v54
	v_ashrrev_i32_e32 v57, 31, v56
	v_ashrrev_i32_e32 v59, 31, v58
	v_ashrrev_i32_e32 v61, 31, v60
	v_ashrrev_i32_e32 v63, 31, v62
	v_ashrrev_i32_e32 v65, 31, v64
	v_ashrrev_i32_e32 v67, 31, v66
	v_ashrrev_i32_e32 v69, 31, v68
	v_ashrrev_i32_e32 v71, 31, v70
	v_ashrrev_i32_e32 v73, 31, v72
	v_ashrrev_i32_e32 v75, 31, v74
	v_ashrrev_i32_e32 v77, 31, v76
	v_ashrrev_i32_e32 v79, 31, v78
	v_lshl_add_u64 v[80:81], s[10:11], 2, v[0:1]
	v_lshlrev_b64 v[18:19], 13, v[18:19]
	v_lshlrev_b64 v[20:21], 13, v[20:21]
	v_lshlrev_b64 v[22:23], 13, v[22:23]
	v_lshlrev_b64 v[24:25], 13, v[24:25]
	v_lshlrev_b64 v[26:27], 13, v[26:27]
	v_lshlrev_b64 v[28:29], 13, v[28:29]
	v_lshlrev_b64 v[30:31], 13, v[30:31]
	v_lshlrev_b64 v[40:41], 13, v[40:41]
	v_lshlrev_b64 v[42:43], 13, v[42:43]
	v_lshlrev_b64 v[32:33], 13, v[32:33]
	v_lshlrev_b64 v[34:35], 13, v[34:35]
	v_lshlrev_b64 v[36:37], 13, v[36:37]
	v_lshlrev_b64 v[38:39], 13, v[38:39]
	v_lshlrev_b64 v[44:45], 13, v[44:45]
	v_lshlrev_b64 v[46:47], 13, v[46:47]
	v_lshlrev_b64 v[48:49], 13, v[48:49]
	v_lshlrev_b64 v[50:51], 13, v[50:51]
	v_lshlrev_b64 v[52:53], 13, v[52:53]
	v_lshlrev_b64 v[54:55], 13, v[54:55]
	v_lshlrev_b64 v[56:57], 13, v[56:57]
	v_lshlrev_b64 v[58:59], 13, v[58:59]
	v_lshlrev_b64 v[60:61], 13, v[60:61]
	v_lshlrev_b64 v[62:63], 13, v[62:63]
	v_lshlrev_b64 v[64:65], 13, v[64:65]
	v_lshlrev_b64 v[66:67], 13, v[66:67]
	v_lshlrev_b64 v[68:69], 13, v[68:69]
	v_lshlrev_b64 v[70:71], 13, v[70:71]
	v_lshlrev_b64 v[72:73], 13, v[72:73]
	v_lshlrev_b64 v[74:75], 13, v[74:75]
	v_lshlrev_b64 v[76:77], 13, v[76:77]
	v_lshlrev_b64 v[78:79], 13, v[78:79]
	v_lshl_add_u64 v[16:17], v[80:81], 0, v[16:17]
	v_lshl_add_u64 v[18:19], v[80:81], 0, v[18:19]
	v_lshl_add_u64 v[20:21], v[80:81], 0, v[20:21]
	v_lshl_add_u64 v[22:23], v[80:81], 0, v[22:23]
	v_lshl_add_u64 v[24:25], v[80:81], 0, v[24:25]
	v_lshl_add_u64 v[26:27], v[80:81], 0, v[26:27]
	v_lshl_add_u64 v[28:29], v[80:81], 0, v[28:29]
	v_lshl_add_u64 v[30:31], v[80:81], 0, v[30:31]
	v_lshl_add_u64 v[40:41], v[80:81], 0, v[40:41]
	v_lshl_add_u64 v[42:43], v[80:81], 0, v[42:43]
	v_lshl_add_u64 v[32:33], v[80:81], 0, v[32:33]
	v_lshl_add_u64 v[34:35], v[80:81], 0, v[34:35]
	v_lshl_add_u64 v[36:37], v[80:81], 0, v[36:37]
	v_lshl_add_u64 v[38:39], v[80:81], 0, v[38:39]
	v_lshl_add_u64 v[44:45], v[80:81], 0, v[44:45]
	v_lshl_add_u64 v[46:47], v[80:81], 0, v[46:47]
	v_lshl_add_u64 v[48:49], v[80:81], 0, v[48:49]
	v_lshl_add_u64 v[50:51], v[80:81], 0, v[50:51]
	v_lshl_add_u64 v[52:53], v[80:81], 0, v[52:53]
	v_lshl_add_u64 v[54:55], v[80:81], 0, v[54:55]
	v_lshl_add_u64 v[56:57], v[80:81], 0, v[56:57]
	v_lshl_add_u64 v[58:59], v[80:81], 0, v[58:59]
	v_lshl_add_u64 v[60:61], v[80:81], 0, v[60:61]
	v_lshl_add_u64 v[62:63], v[80:81], 0, v[62:63]
	v_lshl_add_u64 v[64:65], v[80:81], 0, v[64:65]
	v_lshl_add_u64 v[66:67], v[80:81], 0, v[66:67]
	v_lshl_add_u64 v[68:69], v[80:81], 0, v[68:69]
	v_lshl_add_u64 v[70:71], v[80:81], 0, v[70:71]
	v_lshl_add_u64 v[72:73], v[80:81], 0, v[72:73]
	v_lshl_add_u64 v[74:75], v[80:81], 0, v[74:75]
	v_lshl_add_u64 v[76:77], v[80:81], 0, v[76:77]
	v_lshl_add_u64 v[78:79], v[80:81], 0, v[78:79]
	global_load_dword v15, v[16:17], off nt
	global_load_dword v80, v[18:19], off nt
	global_load_dword v81, v[20:21], off nt
	global_load_dword v82, v[22:23], off nt
	global_load_dword v83, v[24:25], off nt
	global_load_dword v84, v[26:27], off nt
	global_load_dword v85, v[28:29], off nt
	global_load_dword v86, v[30:31], off nt
	global_load_dword v87, v[32:33], off nt
	global_load_dword v88, v[34:35], off nt
	global_load_dword v89, v[36:37], off nt
	global_load_dword v90, v[38:39], off nt
	global_load_dword v91, v[40:41], off nt
	global_load_dword v92, v[42:43], off nt
	global_load_dword v93, v[44:45], off nt
	global_load_dword v18, v[46:47], off nt
	global_load_dword v19, v[48:49], off nt
	global_load_dword v20, v[50:51], off nt
	global_load_dword v21, v[52:53], off nt
	global_load_dword v22, v[54:55], off nt
	global_load_dword v23, v[56:57], off nt
	global_load_dword v24, v[58:59], off nt
	global_load_dword v25, v[60:61], off nt
	global_load_dword v26, v[62:63], off nt
	global_load_dword v27, v[64:65], off nt
	global_load_dword v28, v[66:67], off nt
	global_load_dword v29, v[68:69], off nt
	global_load_dword v30, v[70:71], off nt
	global_load_dword v31, v[72:73], off nt
	global_load_dword v40, v[74:75], off nt
	global_load_dword v41, v[76:77], off nt
	global_load_dword v42, v[78:79], off nt
	s_waitcnt vmcnt(30)
; __device__ __forceinline__ unsigned cvt_pk_bf16(float lo, float hi) { const f32x2c v = {lo, hi}; const bf16x2c b = __builtin_convertvector(v, bf16x2c); return __builtin_bit_cast(unsigned, b); }
; #define LAS __attribute__((address_space(3)))
; template <int MODE> __device__ __forceinline__ void transpose_item(const float* W, int K, int N, bf16_t* WT, LAS float* scr, int item, int lane) {
;     ...
;     for (int i = 0; i < 32; ++i) scr[(2 * i + (lane >> 5)) * 33 + (lane & 31)] = tv[i];
;     asm volatile("s_waitcnt lgkmcnt(0)" ::: "memory");
;     const int c = lane & 7, dr0 = dest_row<MODE>(n0);
; #pragma unroll
;     for (int j = 0; j < 4; ++j) { const int n = (lane >> 3) + 8 * j; const LAS float* s = scr + (8 * c) * 33 + n;
;         u32x4 o; o.x = cvt_pk_bf16(s[0 * 33], s[1 * 33]); o.y = cvt_pk_bf16(s[2 * 33], s[3 * 33]); o.z = cvt_pk_bf16(s[4 * 33], s[5 * 33]); o.w = cvt_pk_bf16(s[6 * 33], s[7 * 33]);
;         *(u32x4*)(WT + (size_t)(dr0 + n) * K + k0 + 8 * c) = o; }
;     asm volatile("s_waitcnt lgkmcnt(0)" ::: "memory");
	ds_write2_b32 v7, v15, v80 offset1:66
	s_waitcnt vmcnt(28)
	ds_write2_b32 v7, v81, v82 offset0:132 offset1:198
	s_waitcnt vmcnt(26)
	ds_write2_b32 v8, v83, v84 offset0:8 offset1:74
	s_waitcnt vmcnt(24)
	ds_write2_b32 v8, v85, v86 offset0:140 offset1:206
	s_waitcnt vmcnt(22)
	ds_write2_b32 v9, v87, v88 offset0:16 offset1:82
	s_waitcnt vmcnt(20)
	ds_write2_b32 v9, v89, v90 offset0:148 offset1:214
	s_waitcnt vmcnt(18)
	ds_write2_b32 v10, v91, v92 offset0:24 offset1:90
	s_waitcnt vmcnt(16)
	ds_write2_b32 v10, v93, v18 offset0:156 offset1:222
	s_waitcnt vmcnt(14)
	ds_write2_b32 v11, v19, v20 offset0:32 offset1:98
	s_waitcnt vmcnt(12)
	ds_write2_b32 v11, v21, v22 offset0:164 offset1:230
	s_waitcnt vmcnt(10)
	ds_write2_b32 v12, v23, v24 offset0:40 offset1:106
	s_waitcnt vmcnt(8)
	ds_write2_b32 v12, v25, v26 offset0:172 offset1:238
	s_waitcnt vmcnt(6)
	ds_write2_b32 v13, v27, v28 offset0:48 offset1:114
	s_waitcnt vmcnt(4)
	ds_write2_b32 v13, v29, v30 offset0:180 offset1:246
	s_waitcnt vmcnt(2)
	ds_write2_b32 v14, v31, v40 offset0:56 offset1:122
	s_waitcnt vmcnt(0)
	ds_write2_b32 v14, v41, v42 offset0:188 offset1:254
	s_waitcnt lgkmcnt(0)
	ds_read2_b32 v[20:21], v6 offset0:33 offset1:41
	ds_read2_b32 v[22:23], v6 offset1:8
	ds_read2_b32 v[24:25], v6 offset0:66 offset1:74
	ds_read2_b32 v[26:27], v6 offset0:99 offset1:107
	ds_read2_b32 v[28:29], v6 offset0:132 offset1:140
	ds_read2_b32 v[30:31], v6 offset0:165 offset1:173
	ds_read2_b32 v[40:41], v6 offset0:198 offset1:206
	ds_read2_b32 v[42:43], v6 offset0:231 offset1:239
	ds_read2_b32 v[44:45], v6 offset0:49 offset1:57
	ds_read2_b32 v[46:47], v6 offset0:16 offset1:24
	ds_read2_b32 v[48:49], v6 offset0:82 offset1:90
	ds_read2_b32 v[50:51], v6 offset0:115 offset1:123
	ds_read2_b32 v[52:53], v6 offset0:148 offset1:156
	ds_read2_b32 v[54:55], v6 offset0:181 offset1:189
	ds_read2_b32 v[56:57], v6 offset0:214 offset1:222
	ds_read2_b32 v[58:59], v6 offset0:247 offset1:255
	s_ashr_i32 s7, s6, 31
	v_add_u32_e32 v34, s10, v5
	v_lshl_add_u64 v[16:17], s[6:7], 1, v[2:3]
	v_add_u32_e32 v35, 8, v34
	v_add_u32_e32 v36, 16, v34
	v_add_u32_e32 v38, 24, v34
	v_mad_i64_i32 v[32:33], s[6:7], v34, s9, v[16:17]
	v_mad_i64_i32 v[34:35], s[6:7], v35, s9, v[16:17]
	v_mad_i64_i32 v[36:37], s[6:7], v36, s9, v[16:17]
	v_mad_i64_i32 v[38:39], s[6:7], v38, s9, v[16:17]
	s_waitcnt lgkmcnt(14)
	v_cvt_pk_bf16_f32 v16, v22, v20
	s_waitcnt lgkmcnt(12)
	v_cvt_pk_bf16_f32 v17, v24, v26
	s_waitcnt lgkmcnt(10)
	v_cvt_pk_bf16_f32 v18, v28, v30
	s_waitcnt lgkmcnt(8)
	v_cvt_pk_bf16_f32 v19, v40, v42
	v_cvt_pk_bf16_f32 v20, v23, v21
	v_cvt_pk_bf16_f32 v21, v25, v27
	v_cvt_pk_bf16_f32 v22, v29, v31
	v_cvt_pk_bf16_f32 v23, v41, v43
	s_waitcnt lgkmcnt(6)
	v_cvt_pk_bf16_f32 v24, v46, v44
	s_waitcnt lgkmcnt(4)
	v_cvt_pk_bf16_f32 v25, v48, v50
	s_waitcnt lgkmcnt(2)
	v_cvt_pk_bf16_f32 v26, v52, v54
	s_waitcnt lgkmcnt(0)
	v_cvt_pk_bf16_f32 v27, v56, v58
	v_cvt_pk_bf16_f32 v28, v47, v45
	v_cvt_pk_bf16_f32 v29, v49, v51
	v_cvt_pk_bf16_f32 v30, v53, v55
	v_cvt_pk_bf16_f32 v31, v57, v59
	global_store_dwordx4 v[32:33], v[16:19], off
	global_store_dwordx4 v[34:35], v[20:23], off
	global_store_dwordx4 v[36:37], v[24:27], off
	global_store_dwordx4 v[38:39], v[28:31], off
	s_waitcnt lgkmcnt(0)
	s_add_i32 s92, s92, s93
	s_add_i32 s3, s3, s8
	s_cmpk_lt_i32 s92, 0x1600
	s_cbranch_scc1 .LBB0_719
